# static s_setprio 1 for waves 4-7 before each GEMM K-loop, per-segment priority flips removed, on top of aligned loop heads
# baseline (speedup 1.0000x reference)
; #define PG8_STAGE(bufoff, gbase, voff) do { _Pragma("unroll") for (int _i = 0; _i < 2; ++_i) \
;         __builtin_amdgcn_global_load_lds((const unsigned*)((const char*)(gbase) + (voff)[_i]), (LAS unsigned*)(lds + (bufoff) + ldsw + _i * 8192), 16, 0, 0); } while (0)
; #define PG8_LDA(dst, b, h) do { _Pragma("unroll") for (int m = 0; m < 4; ++m) _Pragma("unroll") for (int k = 0; k < 2; ++k) dst[m][k] = *(const LAS bf16x8*)(lds + PG8_SA(b, h) + aoff + m * 2048 + k * 1024); } while (0)
; #define PG8_LDB(dst, b, h) do { _Pragma("unroll") for (int n = 0; n < 2; ++n) _Pragma("unroll") for (int k = 0; k < 2; ++k) dst[n][k] = *(const LAS bf16x8*)(lds + PG8_SB(b, h) + boff + n * 2048 + k * 1024); } while (0)
; #define PG8_SCHED __builtin_amdgcn_sched_barrier(0)
; template <class Epi, class Sched>
; __device__ __forceinline__ void gemm_phase(LAS unsigned char* lds, const Gemm g, const Sched& S, const Epi& E) {
;     ...
;         const char* nA = has_next ? (const char*)g.A + (size_t)nxt.pm * tstep + nko : cA; const char* nB = has_next ? (const char*)g.Bt + (size_t)nxt.pn * tstep + nko : cB;
;         const int nt = cur.kc >= 0 ? nts : ntf;
;         for (int t = 0; t < nt; t += 2) {
;             const bool last = (t == nt - 2);
;             const char* a1 = cA + (size_t)(t + 1) * kstep;
;             const char* a2 = last ? nA : cA + (size_t)(t + 2) * kstep; const char* b2 = last ? nB : cB + (size_t)(t + 2) * kstep;
;             const char* a3 = a2 + kstep; const char* b3 = b2 + kstep;
;             PG8_LDB(B0, 0, 0); PG8_LDB(B1, 0, 1); PG8_SCHED; PG8_LDA(At, 0, 0); PG8_STAGE(PG8_SA(1, 1), a1 + hstep, voffA);
;     ...
;         for (int a = 0; a < 2; ++a)
; #pragma unroll
;             for (int b = 0; b < 2; ++b)
; #pragma unroll
;                 for (int m = 0; m < 4; ++m)
; #pragma unroll
;                     for (int n = 0; n < 2; ++n) acc[a][b][m][n] = (f32x4){0.f, 0.f, 0.f, 0.f};
.LBB0_502:
	s_ashr_i32 s51, s50, 31
	s_lshl_b64 s[12:13], s[50:51], 19
	s_add_u32 s54, s92, s12
	s_addc_u32 s55, s93, s13
	s_and_b64 s[12:13], s[38:39], exec
	s_cselect_b32 s7, s55, s15
	s_cselect_b32 s8, s54, s14
	s_ashr_i32 s53, s52, 31
	s_lshl_b64 s[12:13], s[52:53], 19
	s_add_u32 s56, s24, s12
	s_addc_u32 s57, s25, s13
	s_and_b64 s[12:13], s[38:39], exec
	s_cselect_b32 s12, s57, s17
	s_cselect_b32 s13, s56, s16
	s_add_u32 s14, s14, 0x40080
	s_addc_u32 s15, s15, 0
	s_add_u32 s21, s16, 0x100
	v_mov_b32_e32 v0, 0
	s_addc_u32 s33, s17, 0
	s_mov_b32 s40, -2
	v_mov_b32_e32 v1, v0
	s_waitcnt lgkmcnt(0)
	v_mov_b32_e32 v2, v0
	v_mov_b32_e32 v3, v0
	v_mov_b32_e32 v4, v0
	v_mov_b32_e32 v5, v0
	v_mov_b32_e32 v6, v0
	v_mov_b32_e32 v7, v0
	v_mov_b32_e32 v16, v0
	v_mov_b32_e32 v17, v0
	v_mov_b32_e32 v18, v0
	v_mov_b32_e32 v19, v0
	v_mov_b32_e32 v20, v0
	v_mov_b32_e32 v21, v0
	v_mov_b32_e32 v22, v0
	v_mov_b32_e32 v23, v0
	v_mov_b32_e32 v32, v0
	v_mov_b32_e32 v33, v0
	v_mov_b32_e32 v34, v0
	v_mov_b32_e32 v35, v0
	v_mov_b32_e32 v36, v0
	v_mov_b32_e32 v37, v0
	v_mov_b32_e32 v38, v0
	v_mov_b32_e32 v39, v0
	v_mov_b32_e32 v48, v0
	v_mov_b32_e32 v49, v0
	v_mov_b32_e32 v50, v0
	v_mov_b32_e32 v51, v0
	v_mov_b32_e32 v52, v0
	v_mov_b32_e32 v53, v0
	v_mov_b32_e32 v54, v0
	v_mov_b32_e32 v55, v0
	v_mov_b32_e32 v8, v0
	v_mov_b32_e32 v9, v0
	v_mov_b32_e32 v10, v0
	v_mov_b32_e32 v11, v0
	v_mov_b32_e32 v12, v0
	v_mov_b32_e32 v13, v0
	v_mov_b32_e32 v14, v0
	v_mov_b32_e32 v15, v0
	v_mov_b32_e32 v24, v0
	v_mov_b32_e32 v25, v0
	v_mov_b32_e32 v26, v0
	v_mov_b32_e32 v27, v0
	v_mov_b32_e32 v28, v0
	v_mov_b32_e32 v29, v0
	v_mov_b32_e32 v30, v0
	v_mov_b32_e32 v31, v0
	v_mov_b32_e32 v40, v0
	v_mov_b32_e32 v41, v0
	v_mov_b32_e32 v42, v0
	v_mov_b32_e32 v43, v0
	v_mov_b32_e32 v44, v0
	v_mov_b32_e32 v45, v0
	v_mov_b32_e32 v46, v0
	v_mov_b32_e32 v47, v0
	v_mov_b32_e32 v56, v0
	v_mov_b32_e32 v57, v0
	v_mov_b32_e32 v58, v0
	v_mov_b32_e32 v59, v0
	v_mov_b32_e32 v60, v0
	v_mov_b32_e32 v61, v0
	v_mov_b32_e32 v62, v0
	v_mov_b32_e32 v63, v0
	v_mov_b32_e32 v64, v0
	v_mov_b32_e32 v65, v0
	v_mov_b32_e32 v66, v0
	v_mov_b32_e32 v67, v0
	v_mov_b32_e32 v68, v0
	v_mov_b32_e32 v69, v0
	v_mov_b32_e32 v70, v0
	v_mov_b32_e32 v71, v0
	v_mov_b32_e32 v96, v0
	v_mov_b32_e32 v97, v0
	v_mov_b32_e32 v98, v0
	v_mov_b32_e32 v99, v0
	v_mov_b32_e32 v100, v0
	v_mov_b32_e32 v101, v0
	v_mov_b32_e32 v102, v0
	v_mov_b32_e32 v103, v0
	v_mov_b32_e32 v112, v0
	v_mov_b32_e32 v113, v0
	v_mov_b32_e32 v114, v0
	v_mov_b32_e32 v115, v0
	v_mov_b32_e32 v116, v0
	v_mov_b32_e32 v117, v0
	v_mov_b32_e32 v118, v0
	v_mov_b32_e32 v119, v0
	v_mov_b32_e32 v128, v0
	v_mov_b32_e32 v129, v0
	v_mov_b32_e32 v130, v0
	v_mov_b32_e32 v131, v0
	v_mov_b32_e32 v132, v0
	v_mov_b32_e32 v133, v0
	v_mov_b32_e32 v134, v0
	v_mov_b32_e32 v135, v0
	v_mov_b32_e32 v88, v0
	v_mov_b32_e32 v89, v0
	v_mov_b32_e32 v90, v0
	v_mov_b32_e32 v91, v0
	v_mov_b32_e32 v92, v0
	v_mov_b32_e32 v93, v0
	v_mov_b32_e32 v94, v0
	v_mov_b32_e32 v95, v0
	v_mov_b32_e32 v104, v0
	v_mov_b32_e32 v105, v0
	v_mov_b32_e32 v106, v0
	v_mov_b32_e32 v107, v0
	v_mov_b32_e32 v108, v0
	v_mov_b32_e32 v109, v0
	v_mov_b32_e32 v110, v0
	v_mov_b32_e32 v111, v0
	v_mov_b32_e32 v120, v0
	v_mov_b32_e32 v121, v0
	v_mov_b32_e32 v122, v0
	v_mov_b32_e32 v123, v0
	v_mov_b32_e32 v124, v0
	v_mov_b32_e32 v125, v0
	v_mov_b32_e32 v126, v0
	v_mov_b32_e32 v127, v0
	v_mov_b32_e32 v136, v0
	v_mov_b32_e32 v137, v0
	v_mov_b32_e32 v138, v0
	v_mov_b32_e32 v139, v0
	v_mov_b32_e32 v140, v0
	v_mov_b32_e32 v141, v0
	v_mov_b32_e32 v142, v0
	v_mov_b32_e32 v143, v0
	s_cmp_lg_u32 s48, 0
	s_cbranch_scc1 .Lprio503_skip
	s_setprio 1
.Lprio503_skip:
	.p2align	6
.LBB0_503:
	s_add_u32 s16, s14, 0xfffc0080
	s_addc_u32 s17, s15, -1
	s_add_i32 s41, 0, 0x10000
	s_cmp_eq_u32 s40, 12
	s_cselect_b32 s19, s7, s17
	s_cselect_b32 s18, s8, s16
	s_cselect_b32 s17, s12, s33
	s_cselect_b32 s16, s13, s21
	s_add_i32 s51, 0, 0x14000
	v_add_u32_e32 v84, s41, v168
	v_add_u32_e32 v170, s51, v168
	ds_read_b128 v[72:75], v84
	ds_read_b128 v[76:79], v84 offset:1024
	ds_read_b128 v[80:83], v84 offset:2048
	ds_read_b128 v[84:87], v84 offset:3072
	ds_read_b128 v[154:157], v170
	ds_read_b128 v[158:161], v170 offset:1024
	ds_read_b128 v[162:165], v170 offset:2048
	ds_read_b128 v[170:173], v170 offset:3072
	v_lshl_add_u64 v[178:179], s[14:15], 0, v[150:151]
	s_add_i32 m0, s26, 0xc000
	ds_read_b128 v[174:177], v169
	ds_read_b128 v[192:195], v169 offset:1024
	ds_read_b128 v[196:199], v169 offset:2048
	ds_read_b128 v[200:203], v169 offset:3072
	ds_read_b128 v[204:207], v169 offset:4096
	ds_read_b128 v[208:211], v169 offset:5120
	ds_read_b128 v[212:215], v169 offset:6144
	ds_read_b128 v[230:233], v169 offset:7168
	global_load_lds_dwordx4 v[178:179], off
	v_lshl_add_u64 v[178:179], s[14:15], 0, v[152:153]
	s_add_i32 m0, s26, 0xe000
	s_nop 0
	global_load_lds_dwordx4 v[178:179], off
	s_waitcnt vmcnt(8)
	s_waitcnt lgkmcnt(0)
	s_barrier
; #define PG8_STAGE(bufoff, gbase, voff) do { _Pragma("unroll") for (int _i = 0; _i < 2; ++_i) \
;         __builtin_amdgcn_global_load_lds((const unsigned*)((const char*)(gbase) + (voff)[_i]), (LAS unsigned*)(lds + (bufoff) + ldsw + _i * 8192), 16, 0, 0); } while (0)
; #define PG8_LDA(dst, b, h) do { _Pragma("unroll") for (int m = 0; m < 4; ++m) _Pragma("unroll") for (int k = 0; k < 2; ++k) dst[m][k] = *(const LAS bf16x8*)(lds + PG8_SA(b, h) + aoff + m * 2048 + k * 1024); } while (0)
; #define PG8_MMA(ai, bj, At, Bt) do { __builtin_amdgcn_s_setprio(1); _Pragma("unroll") for (int m = 0; m < 4; ++m) _Pragma("unroll") for (int n = 0; n < 2; ++n) _Pragma("unroll") for (int k = 0; k < 2; ++k) \
;         acc[ai][bj][m][n] = __builtin_amdgcn_mfma_f32_16x16x32_bf16(Bt[n][k], At[m][k], acc[ai][bj][m][n], 0, 0, 0); __builtin_amdgcn_s_setprio(0); } while (0)
; #define PG8_WAIT_V(n) asm volatile("s_waitcnt vmcnt(" #n ")" ::: "memory")
; #define PG8_WAIT_L(n) asm volatile("s_waitcnt lgkmcnt(" #n ")" ::: "memory")
; #define PG8_BAR __builtin_amdgcn_s_barrier()
; #define PG8_SCHED __builtin_amdgcn_sched_barrier(0)
; template <class Epi, class Sched>
; __device__ __forceinline__ void gemm_phase(LAS unsigned char* lds, const Gemm g, const Sched& S, const Epi& E) {
;     ...
;             PG8_WAIT_V(8); PG8_WAIT_L(0); PG8_BAR; PG8_MMA(0, 0, At, B0); PG8_MMA(0, 1, At, B1); PG8_BAR; PG8_SCHED;
;             PG8_LDA(At, 0, 1); PG8_STAGE(PG8_SB(0, 0), b2, voffB); PG8_STAGE(PG8_SB(0, 1), b2 + hstep, voffB); PG8_STAGE(PG8_SA(0, 0), a2, voffA);
;             PG8_WAIT_V(8); PG8_WAIT_L(0); PG8_BAR; PG8_MMA(1, 0, At, B0); PG8_MMA(1, 1, At, B1); PG8_BAR; PG8_SCHED;
	s_waitcnt lgkmcnt(0)
	v_mfma_f32_16x16x32_bf16 v[140:143], v[72:75], v[174:177], v[140:143]
	v_mfma_f32_16x16x32_bf16 v[136:139], v[80:83], v[174:177], v[136:139]
	v_mfma_f32_16x16x32_bf16 v[124:127], v[72:75], v[196:199], v[124:127]
	v_mfma_f32_16x16x32_bf16 v[120:123], v[80:83], v[196:199], v[120:123]
	v_mfma_f32_16x16x32_bf16 v[108:111], v[72:75], v[204:207], v[108:111]
	v_mfma_f32_16x16x32_bf16 v[104:107], v[80:83], v[204:207], v[104:107]
	v_mfma_f32_16x16x32_bf16 v[92:95], v[72:75], v[212:215], v[92:95]
	v_mfma_f32_16x16x32_bf16 v[88:91], v[80:83], v[212:215], v[88:91]
	v_mfma_f32_16x16x32_bf16 v[140:143], v[76:79], v[192:195], v[140:143]
	v_mfma_f32_16x16x32_bf16 v[136:139], v[84:87], v[192:195], v[136:139]
	v_mfma_f32_16x16x32_bf16 v[124:127], v[76:79], v[200:203], v[124:127]
	v_mfma_f32_16x16x32_bf16 v[120:123], v[84:87], v[200:203], v[120:123]
	v_mfma_f32_16x16x32_bf16 v[108:111], v[76:79], v[208:211], v[108:111]
	v_mfma_f32_16x16x32_bf16 v[104:107], v[84:87], v[208:211], v[104:107]
	v_mfma_f32_16x16x32_bf16 v[92:95], v[76:79], v[230:233], v[92:95]
	v_mfma_f32_16x16x32_bf16 v[88:91], v[84:87], v[230:233], v[88:91]
	v_mfma_f32_16x16x32_bf16 v[132:135], v[154:157], v[174:177], v[132:135]
	v_mfma_f32_16x16x32_bf16 v[128:131], v[162:165], v[174:177], v[128:131]
	v_mfma_f32_16x16x32_bf16 v[116:119], v[154:157], v[196:199], v[116:119]
	v_mfma_f32_16x16x32_bf16 v[112:115], v[162:165], v[196:199], v[112:115]
	v_mfma_f32_16x16x32_bf16 v[100:103], v[154:157], v[204:207], v[100:103]
	v_mfma_f32_16x16x32_bf16 v[96:99], v[162:165], v[204:207], v[96:99]
	v_mfma_f32_16x16x32_bf16 v[68:71], v[154:157], v[212:215], v[68:71]
	v_mfma_f32_16x16x32_bf16 v[64:67], v[162:165], v[212:215], v[64:67]
	v_mfma_f32_16x16x32_bf16 v[132:135], v[158:161], v[192:195], v[132:135]
	v_mfma_f32_16x16x32_bf16 v[128:131], v[170:173], v[192:195], v[128:131]
	v_mfma_f32_16x16x32_bf16 v[116:119], v[158:161], v[200:203], v[116:119]
	v_mfma_f32_16x16x32_bf16 v[112:115], v[170:173], v[200:203], v[112:115]
	v_mfma_f32_16x16x32_bf16 v[100:103], v[158:161], v[208:211], v[100:103]
	v_mfma_f32_16x16x32_bf16 v[96:99], v[170:173], v[208:211], v[96:99]
	v_mfma_f32_16x16x32_bf16 v[68:71], v[158:161], v[230:233], v[68:71]
	v_mfma_f32_16x16x32_bf16 v[64:67], v[170:173], v[230:233], v[64:67]
	s_barrier
	s_add_i32 s41, s41, s23
	v_lshl_add_u64 v[178:179], s[16:17], 0, v[184:185]
	s_mov_b32 m0, s41
	ds_read_b128 v[174:177], v169 offset:16384
	ds_read_b128 v[192:195], v169 offset:17408
	ds_read_b128 v[196:199], v169 offset:18432
	ds_read_b128 v[200:203], v169 offset:19456
	ds_read_b128 v[204:207], v169 offset:20480
	ds_read_b128 v[208:211], v169 offset:21504
	ds_read_b128 v[212:215], v169 offset:22528
	ds_read_b128 v[230:233], v169 offset:23552
	global_load_lds_dwordx4 v[178:179], off
	s_add_i32 m0, s41, 0x2000
	s_add_u32 s42, s16, 0x40000
	v_lshl_add_u64 v[216:217], s[16:17], 0, v[148:149]
	s_addc_u32 s43, s17, 0
	s_add_i32 s41, s51, s23
	global_load_lds_dwordx4 v[216:217], off
	v_lshl_add_u64 v[234:235], s[42:43], 0, v[184:185]
	s_mov_b32 m0, s41
	v_lshl_add_u64 v[236:237], s[18:19], 0, v[146:147]
	global_load_lds_dwordx4 v[234:235], off
	v_lshl_add_u64 v[234:235], s[42:43], 0, v[148:149]
	s_add_i32 m0, s41, 0x2000
	s_nop 0
	global_load_lds_dwordx4 v[234:235], off
	v_lshl_add_u64 v[234:235], s[18:19], 0, v[144:145]
	s_mov_b32 m0, s26
	s_nop 0
	global_load_lds_dwordx4 v[234:235], off
	s_mov_b32 m0, s27
	s_nop 0
	global_load_lds_dwordx4 v[236:237], off
	s_waitcnt vmcnt(8)
	s_waitcnt lgkmcnt(0)
	s_barrier
	s_waitcnt lgkmcnt(0)
	v_mfma_f32_16x16x32_bf16 v[60:63], v[72:75], v[174:177], v[60:63]
	v_mfma_f32_16x16x32_bf16 v[56:59], v[80:83], v[174:177], v[56:59]
	v_mfma_f32_16x16x32_bf16 v[44:47], v[72:75], v[196:199], v[44:47]
	v_mfma_f32_16x16x32_bf16 v[40:43], v[80:83], v[196:199], v[40:43]
	v_mfma_f32_16x16x32_bf16 v[28:31], v[72:75], v[204:207], v[28:31]
	v_mfma_f32_16x16x32_bf16 v[24:27], v[80:83], v[204:207], v[24:27]
	v_mfma_f32_16x16x32_bf16 v[12:15], v[72:75], v[212:215], v[12:15]
	v_mfma_f32_16x16x32_bf16 v[8:11], v[80:83], v[212:215], v[8:11]
	v_mfma_f32_16x16x32_bf16 v[60:63], v[76:79], v[192:195], v[60:63]
	v_mfma_f32_16x16x32_bf16 v[56:59], v[84:87], v[192:195], v[56:59]
	v_mfma_f32_16x16x32_bf16 v[44:47], v[76:79], v[200:203], v[44:47]
	v_mfma_f32_16x16x32_bf16 v[40:43], v[84:87], v[200:203], v[40:43]
	v_mfma_f32_16x16x32_bf16 v[28:31], v[76:79], v[208:211], v[28:31]
	v_mfma_f32_16x16x32_bf16 v[24:27], v[84:87], v[208:211], v[24:27]
	v_mfma_f32_16x16x32_bf16 v[12:15], v[76:79], v[230:233], v[12:15]
	v_mfma_f32_16x16x32_bf16 v[8:11], v[84:87], v[230:233], v[8:11]
	v_mfma_f32_16x16x32_bf16 v[52:55], v[154:157], v[174:177], v[52:55]
	v_mfma_f32_16x16x32_bf16 v[48:51], v[162:165], v[174:177], v[48:51]
	v_mfma_f32_16x16x32_bf16 v[36:39], v[154:157], v[196:199], v[36:39]
	v_mfma_f32_16x16x32_bf16 v[32:35], v[162:165], v[196:199], v[32:35]
	v_mfma_f32_16x16x32_bf16 v[20:23], v[154:157], v[204:207], v[20:23]
	v_mfma_f32_16x16x32_bf16 v[16:19], v[162:165], v[204:207], v[16:19]
	v_mfma_f32_16x16x32_bf16 v[4:7], v[154:157], v[212:215], v[4:7]
	v_mfma_f32_16x16x32_bf16 v[0:3], v[162:165], v[212:215], v[0:3]
	v_mfma_f32_16x16x32_bf16 v[52:55], v[158:161], v[192:195], v[52:55]
	v_mfma_f32_16x16x32_bf16 v[48:51], v[170:173], v[192:195], v[48:51]
	v_mfma_f32_16x16x32_bf16 v[36:39], v[158:161], v[200:203], v[36:39]
	v_mfma_f32_16x16x32_bf16 v[32:35], v[170:173], v[200:203], v[32:35]
	v_mfma_f32_16x16x32_bf16 v[20:23], v[158:161], v[208:211], v[20:23]
	v_mfma_f32_16x16x32_bf16 v[16:19], v[170:173], v[208:211], v[16:19]
	v_mfma_f32_16x16x32_bf16 v[4:7], v[158:161], v[230:233], v[4:7]
	v_mfma_f32_16x16x32_bf16 v[0:3], v[170:173], v[230:233], v[0:3]
	s_barrier
; #define PG8_STAGE(bufoff, gbase, voff) do { _Pragma("unroll") for (int _i = 0; _i < 2; ++_i) \
;         __builtin_amdgcn_global_load_lds((const unsigned*)((const char*)(gbase) + (voff)[_i]), (LAS unsigned*)(lds + (bufoff) + ldsw + _i * 8192), 16, 0, 0); } while (0)
; #define PG8_LDA(dst, b, h) do { _Pragma("unroll") for (int m = 0; m < 4; ++m) _Pragma("unroll") for (int k = 0; k < 2; ++k) dst[m][k] = *(const LAS bf16x8*)(lds + PG8_SA(b, h) + aoff + m * 2048 + k * 1024); } while (0)
; #define PG8_LDB(dst, b, h) do { _Pragma("unroll") for (int n = 0; n < 2; ++n) _Pragma("unroll") for (int k = 0; k < 2; ++k) dst[n][k] = *(const LAS bf16x8*)(lds + PG8_SB(b, h) + boff + n * 2048 + k * 1024); } while (0)
; #define PG8_MMA(ai, bj, At, Bt) do { __builtin_amdgcn_s_setprio(1); _Pragma("unroll") for (int m = 0; m < 4; ++m) _Pragma("unroll") for (int n = 0; n < 2; ++n) _Pragma("unroll") for (int k = 0; k < 2; ++k) \
;         acc[ai][bj][m][n] = __builtin_amdgcn_mfma_f32_16x16x32_bf16(Bt[n][k], At[m][k], acc[ai][bj][m][n], 0, 0, 0); __builtin_amdgcn_s_setprio(0); } while (0)
; #define PG8_WAIT_V(n) asm volatile("s_waitcnt vmcnt(" #n ")" ::: "memory")
; #define PG8_WAIT_L(n) asm volatile("s_waitcnt lgkmcnt(" #n ")" ::: "memory")
; #define PG8_BAR __builtin_amdgcn_s_barrier()
; #define PG8_SCHED __builtin_amdgcn_sched_barrier(0)
; template <class Epi, class Sched>
; __device__ __forceinline__ void gemm_phase(LAS unsigned char* lds, const Gemm g, const Sched& S, const Epi& E) {
;     ...
;             PG8_LDB(B0, 1, 0); PG8_LDB(B1, 1, 1); PG8_SCHED; PG8_LDA(At, 1, 0); PG8_STAGE(PG8_SA(0, 1), a2 + hstep, voffA);
;             PG8_WAIT_V(8); PG8_WAIT_L(0); PG8_BAR; PG8_MMA(0, 0, At, B0); PG8_MMA(0, 1, At, B1); PG8_BAR; PG8_SCHED;
	s_add_i32 s41, 0, 0x18000
	s_add_i32 s42, 0, 0x1c000
	v_add_u32_e32 v84, s41, v168
	v_add_u32_e32 v170, s42, v168
	ds_read_b128 v[72:75], v84
	ds_read_b128 v[76:79], v84 offset:1024
	ds_read_b128 v[80:83], v84 offset:2048
	ds_read_b128 v[84:87], v84 offset:3072
	ds_read_b128 v[154:157], v170
	ds_read_b128 v[158:161], v170 offset:1024
	ds_read_b128 v[162:165], v170 offset:2048
	ds_read_b128 v[170:173], v170 offset:3072
	s_add_u32 s18, s18, 0x40000
	s_addc_u32 s19, s19, 0
	s_mov_b32 m0, s28
	v_lshl_add_u64 v[238:239], s[18:19], 0, v[144:145]
	ds_read_b128 v[174:177], v169 offset:32768
	ds_read_b128 v[192:195], v169 offset:33792
	ds_read_b128 v[196:199], v169 offset:34816
	ds_read_b128 v[200:203], v169 offset:35840
	ds_read_b128 v[204:207], v169 offset:36864
	ds_read_b128 v[208:211], v169 offset:37888
	ds_read_b128 v[212:215], v169 offset:38912
	ds_read_b128 v[230:233], v169 offset:39936
	global_load_lds_dwordx4 v[238:239], off
	v_lshl_add_u64 v[238:239], s[18:19], 0, v[146:147]
	s_mov_b32 m0, s29
	s_nop 0
	global_load_lds_dwordx4 v[238:239], off
	s_waitcnt vmcnt(8)
	s_waitcnt lgkmcnt(0)
	s_barrier
	s_waitcnt lgkmcnt(0)
	v_mfma_f32_16x16x32_bf16 v[140:143], v[72:75], v[174:177], v[140:143]
	v_mfma_f32_16x16x32_bf16 v[136:139], v[80:83], v[174:177], v[136:139]
	v_mfma_f32_16x16x32_bf16 v[124:127], v[72:75], v[196:199], v[124:127]
	v_mfma_f32_16x16x32_bf16 v[120:123], v[80:83], v[196:199], v[120:123]
	v_mfma_f32_16x16x32_bf16 v[108:111], v[72:75], v[204:207], v[108:111]
	v_mfma_f32_16x16x32_bf16 v[104:107], v[80:83], v[204:207], v[104:107]
	v_mfma_f32_16x16x32_bf16 v[92:95], v[72:75], v[212:215], v[92:95]
	v_mfma_f32_16x16x32_bf16 v[88:91], v[80:83], v[212:215], v[88:91]
	v_mfma_f32_16x16x32_bf16 v[140:143], v[76:79], v[192:195], v[140:143]
	v_mfma_f32_16x16x32_bf16 v[136:139], v[84:87], v[192:195], v[136:139]
	v_mfma_f32_16x16x32_bf16 v[124:127], v[76:79], v[200:203], v[124:127]
	v_mfma_f32_16x16x32_bf16 v[120:123], v[84:87], v[200:203], v[120:123]
	v_mfma_f32_16x16x32_bf16 v[108:111], v[76:79], v[208:211], v[108:111]
	v_mfma_f32_16x16x32_bf16 v[104:107], v[84:87], v[208:211], v[104:107]
	v_mfma_f32_16x16x32_bf16 v[92:95], v[76:79], v[230:233], v[92:95]
	v_mfma_f32_16x16x32_bf16 v[88:91], v[84:87], v[230:233], v[88:91]
	v_mfma_f32_16x16x32_bf16 v[132:135], v[154:157], v[174:177], v[132:135]
	v_mfma_f32_16x16x32_bf16 v[128:131], v[162:165], v[174:177], v[128:131]
	v_mfma_f32_16x16x32_bf16 v[116:119], v[154:157], v[196:199], v[116:119]
	v_mfma_f32_16x16x32_bf16 v[112:115], v[162:165], v[196:199], v[112:115]
	v_mfma_f32_16x16x32_bf16 v[100:103], v[154:157], v[204:207], v[100:103]
	v_mfma_f32_16x16x32_bf16 v[96:99], v[162:165], v[204:207], v[96:99]
	v_mfma_f32_16x16x32_bf16 v[68:71], v[154:157], v[212:215], v[68:71]
	v_mfma_f32_16x16x32_bf16 v[64:67], v[162:165], v[212:215], v[64:67]
	v_mfma_f32_16x16x32_bf16 v[132:135], v[158:161], v[192:195], v[132:135]
	v_mfma_f32_16x16x32_bf16 v[128:131], v[170:173], v[192:195], v[128:131]
	v_mfma_f32_16x16x32_bf16 v[116:119], v[158:161], v[200:203], v[116:119]
	v_mfma_f32_16x16x32_bf16 v[112:115], v[170:173], v[200:203], v[112:115]
	v_mfma_f32_16x16x32_bf16 v[100:103], v[158:161], v[208:211], v[100:103]
	v_mfma_f32_16x16x32_bf16 v[96:99], v[170:173], v[208:211], v[96:99]
	v_mfma_f32_16x16x32_bf16 v[68:71], v[158:161], v[230:233], v[68:71]
	v_mfma_f32_16x16x32_bf16 v[64:67], v[170:173], v[230:233], v[64:67]
	s_barrier
; #define PG8_STAGE(bufoff, gbase, voff) do { _Pragma("unroll") for (int _i = 0; _i < 2; ++_i) \
;         __builtin_amdgcn_global_load_lds((const unsigned*)((const char*)(gbase) + (voff)[_i]), (LAS unsigned*)(lds + (bufoff) + ldsw + _i * 8192), 16, 0, 0); } while (0)
; #define PG8_LDA(dst, b, h) do { _Pragma("unroll") for (int m = 0; m < 4; ++m) _Pragma("unroll") for (int k = 0; k < 2; ++k) dst[m][k] = *(const LAS bf16x8*)(lds + PG8_SA(b, h) + aoff + m * 2048 + k * 1024); } while (0)
; #define PG8_MMA(ai, bj, At, Bt) do { __builtin_amdgcn_s_setprio(1); _Pragma("unroll") for (int m = 0; m < 4; ++m) _Pragma("unroll") for (int n = 0; n < 2; ++n) _Pragma("unroll") for (int k = 0; k < 2; ++k) \
;         acc[ai][bj][m][n] = __builtin_amdgcn_mfma_f32_16x16x32_bf16(Bt[n][k], At[m][k], acc[ai][bj][m][n], 0, 0, 0); __builtin_amdgcn_s_setprio(0); } while (0)
; #define PG8_WAIT_V(n) asm volatile("s_waitcnt vmcnt(" #n ")" ::: "memory")
; #define PG8_WAIT_L(n) asm volatile("s_waitcnt lgkmcnt(" #n ")" ::: "memory")
; #define PG8_BAR __builtin_amdgcn_s_barrier()
; #define PG8_SCHED __builtin_amdgcn_sched_barrier(0)
; template <class Epi, class Sched>
; __device__ __forceinline__ void gemm_phase(LAS unsigned char* lds, const Gemm g, const Sched& S, const Epi& E) {
;     ...
;             PG8_LDA(At, 1, 1); PG8_STAGE(PG8_SB(1, 0), b3, voffB); PG8_STAGE(PG8_SB(1, 1), b3 + hstep, voffB); PG8_STAGE(PG8_SA(1, 0), a3, voffA);
;             PG8_WAIT_V(8); PG8_WAIT_L(0); PG8_BAR; PG8_MMA(1, 0, At, B0); PG8_MMA(1, 1, At, B1); PG8_BAR; PG8_SCHED;
;         }
;         if (wr == 0) PG8_BAR;
	s_add_i32 s18, s41, s23
	v_lshl_add_u64 v[178:179], v[178:179], 0, s[84:85]
	s_mov_b32 m0, s18
	ds_read_b128 v[174:177], v169 offset:49152
	ds_read_b128 v[192:195], v169 offset:50176
	ds_read_b128 v[196:199], v169 offset:51200
	ds_read_b128 v[200:203], v169 offset:52224
	ds_read_b128 v[204:207], v169 offset:53248
	ds_read_b128 v[208:211], v169 offset:54272
	ds_read_b128 v[212:215], v169 offset:55296
	ds_read_b128 v[230:233], v169 offset:56320
	global_load_lds_dwordx4 v[178:179], off
	s_add_i32 m0, s18, 0x2000
	s_add_u32 s16, s16, 0x40080
	v_lshl_add_u64 v[178:179], v[216:217], 0, s[84:85]
	s_addc_u32 s17, s17, 0
	s_add_i32 s18, s42, s23
	global_load_lds_dwordx4 v[178:179], off
	v_lshl_add_u64 v[178:179], s[16:17], 0, v[184:185]
	s_mov_b32 m0, s18
	s_nop 0
	global_load_lds_dwordx4 v[178:179], off
	v_lshl_add_u64 v[178:179], s[16:17], 0, v[148:149]
	s_add_i32 m0, s18, 0x2000
	s_nop 0
	global_load_lds_dwordx4 v[178:179], off
	v_lshl_add_u64 v[178:179], v[234:235], 0, s[84:85]
	s_mov_b32 m0, s34
	s_nop 0
	global_load_lds_dwordx4 v[178:179], off
	v_lshl_add_u64 v[178:179], v[236:237], 0, s[84:85]
	s_mov_b32 m0, s35
	s_nop 0
	global_load_lds_dwordx4 v[178:179], off
	s_waitcnt vmcnt(8)
	s_waitcnt lgkmcnt(0)
	s_barrier
	s_waitcnt lgkmcnt(0)
	v_mfma_f32_16x16x32_bf16 v[60:63], v[72:75], v[174:177], v[60:63]
	v_mfma_f32_16x16x32_bf16 v[56:59], v[80:83], v[174:177], v[56:59]
	v_mfma_f32_16x16x32_bf16 v[44:47], v[72:75], v[196:199], v[44:47]
	v_mfma_f32_16x16x32_bf16 v[40:43], v[80:83], v[196:199], v[40:43]
	v_mfma_f32_16x16x32_bf16 v[28:31], v[72:75], v[204:207], v[28:31]
	v_mfma_f32_16x16x32_bf16 v[24:27], v[80:83], v[204:207], v[24:27]
	v_mfma_f32_16x16x32_bf16 v[12:15], v[72:75], v[212:215], v[12:15]
	v_mfma_f32_16x16x32_bf16 v[8:11], v[80:83], v[212:215], v[8:11]
	v_mfma_f32_16x16x32_bf16 v[60:63], v[76:79], v[192:195], v[60:63]
	v_mfma_f32_16x16x32_bf16 v[56:59], v[84:87], v[192:195], v[56:59]
	v_mfma_f32_16x16x32_bf16 v[44:47], v[76:79], v[200:203], v[44:47]
	v_mfma_f32_16x16x32_bf16 v[40:43], v[84:87], v[200:203], v[40:43]
	v_mfma_f32_16x16x32_bf16 v[28:31], v[76:79], v[208:211], v[28:31]
	v_mfma_f32_16x16x32_bf16 v[24:27], v[84:87], v[208:211], v[24:27]
	v_mfma_f32_16x16x32_bf16 v[12:15], v[76:79], v[230:233], v[12:15]
	v_mfma_f32_16x16x32_bf16 v[8:11], v[84:87], v[230:233], v[8:11]
	v_mfma_f32_16x16x32_bf16 v[52:55], v[154:157], v[174:177], v[52:55]
	v_mfma_f32_16x16x32_bf16 v[48:51], v[162:165], v[174:177], v[48:51]
	v_mfma_f32_16x16x32_bf16 v[36:39], v[154:157], v[196:199], v[36:39]
	v_mfma_f32_16x16x32_bf16 v[32:35], v[162:165], v[196:199], v[32:35]
	v_mfma_f32_16x16x32_bf16 v[20:23], v[154:157], v[204:207], v[20:23]
	v_mfma_f32_16x16x32_bf16 v[16:19], v[162:165], v[204:207], v[16:19]
	v_mfma_f32_16x16x32_bf16 v[4:7], v[154:157], v[212:215], v[4:7]
	v_mfma_f32_16x16x32_bf16 v[0:3], v[162:165], v[212:215], v[0:3]
	v_mfma_f32_16x16x32_bf16 v[52:55], v[158:161], v[192:195], v[52:55]
	v_mfma_f32_16x16x32_bf16 v[48:51], v[170:173], v[192:195], v[48:51]
	v_mfma_f32_16x16x32_bf16 v[36:39], v[158:161], v[200:203], v[36:39]
	v_mfma_f32_16x16x32_bf16 v[32:35], v[170:173], v[200:203], v[32:35]
	v_mfma_f32_16x16x32_bf16 v[20:23], v[158:161], v[208:211], v[20:23]
	v_mfma_f32_16x16x32_bf16 v[16:19], v[170:173], v[208:211], v[16:19]
	v_mfma_f32_16x16x32_bf16 v[4:7], v[158:161], v[230:233], v[4:7]
	v_mfma_f32_16x16x32_bf16 v[0:3], v[170:173], v[230:233], v[0:3]
	s_barrier
	s_add_i32 s40, s40, 2
	s_add_u32 s14, s14, 0x100
	s_addc_u32 s15, s15, 0
	s_add_u32 s21, s21, 0x100
	s_addc_u32 s33, s33, 0
	s_cmp_gt_u32 s40, 13
	s_cbranch_scc0 .LBB0_503
	s_setprio 0
	s_and_b64 vcc, exec, s[48:49]
	s_cbranch_vccz .LBB0_506
	s_barrier

; template <class Epi, class Sched>
; __device__ __forceinline__ void gemm_phase(LAS unsigned char* lds, const Gemm g, const Sched& S, const Epi& E) {
;     ...
;         const int nt = cur.kc >= 0 ? nts : ntf;
;         for (int t = 0; t < nt; t += 2) {
;     ...
;         for (int a = 0; a < 2; ++a)
; #pragma unroll
;             for (int b = 0; b < 2; ++b)
; #pragma unroll
;                 for (int m = 0; m < 4; ++m)
; #pragma unroll
;                     for (int n = 0; n < 2; ++n) acc[a][b][m][n] = (f32x4){0.f, 0.f, 0.f, 0.f};
.LBB0_598:
	s_cmp_lt_i32 s78, 0
	s_cselect_b32 s8, s22, s23
	s_add_i32 s12, s8, -2
	s_add_u32 s6, s6, 0x80
	s_addc_u32 s7, s7, 0
	s_add_u32 s13, s14, 0x100
	v_mov_b32_e32 v0, 0
	s_mov_b32 s17, 0
	s_addc_u32 s16, s15, 0
	v_mov_b32_e32 v1, v0
	v_mov_b32_e32 v2, v0
	v_mov_b32_e32 v3, v0
	v_mov_b32_e32 v4, v0
	v_mov_b32_e32 v5, v0
	v_mov_b32_e32 v6, v0
	v_mov_b32_e32 v7, v0
	v_mov_b32_e32 v8, v0
	v_mov_b32_e32 v9, v0
	v_mov_b32_e32 v10, v0
	v_mov_b32_e32 v11, v0
	v_mov_b32_e32 v12, v0
	v_mov_b32_e32 v13, v0
	v_mov_b32_e32 v14, v0
	v_mov_b32_e32 v15, v0
	v_mov_b32_e32 v24, v0
	v_mov_b32_e32 v25, v0
	v_mov_b32_e32 v26, v0
	v_mov_b32_e32 v27, v0
	v_mov_b32_e32 v28, v0
	v_mov_b32_e32 v29, v0
	v_mov_b32_e32 v30, v0
	v_mov_b32_e32 v31, v0
	v_mov_b32_e32 v40, v0
	v_mov_b32_e32 v41, v0
	v_mov_b32_e32 v42, v0
	v_mov_b32_e32 v43, v0
	v_mov_b32_e32 v44, v0
	v_mov_b32_e32 v45, v0
	v_mov_b32_e32 v46, v0
	v_mov_b32_e32 v47, v0
	v_mov_b32_e32 v16, v0
	v_mov_b32_e32 v17, v0
	v_mov_b32_e32 v18, v0
	v_mov_b32_e32 v19, v0
	v_mov_b32_e32 v20, v0
	v_mov_b32_e32 v21, v0
	v_mov_b32_e32 v22, v0
	v_mov_b32_e32 v23, v0
	v_mov_b32_e32 v32, v0
	v_mov_b32_e32 v33, v0
	v_mov_b32_e32 v34, v0
	v_mov_b32_e32 v35, v0
	v_mov_b32_e32 v36, v0
	v_mov_b32_e32 v37, v0
	v_mov_b32_e32 v38, v0
	v_mov_b32_e32 v39, v0
	v_mov_b32_e32 v48, v0
	v_mov_b32_e32 v49, v0
	v_mov_b32_e32 v50, v0
	v_mov_b32_e32 v51, v0
	v_mov_b32_e32 v52, v0
	v_mov_b32_e32 v53, v0
	v_mov_b32_e32 v54, v0
	v_mov_b32_e32 v55, v0
	v_mov_b32_e32 v56, v0
	v_mov_b32_e32 v57, v0
	v_mov_b32_e32 v58, v0
	v_mov_b32_e32 v59, v0
	v_mov_b32_e32 v60, v0
	v_mov_b32_e32 v61, v0
	v_mov_b32_e32 v62, v0
	v_mov_b32_e32 v63, v0
	v_mov_b32_e32 v64, v0
	v_mov_b32_e32 v65, v0
	v_mov_b32_e32 v66, v0
	v_mov_b32_e32 v67, v0
	v_mov_b32_e32 v68, v0
	v_mov_b32_e32 v69, v0
	v_mov_b32_e32 v70, v0
	v_mov_b32_e32 v71, v0
	v_mov_b32_e32 v72, v0
	v_mov_b32_e32 v73, v0
	v_mov_b32_e32 v74, v0
	v_mov_b32_e32 v75, v0
	v_mov_b32_e32 v76, v0
	v_mov_b32_e32 v77, v0
	v_mov_b32_e32 v78, v0
	v_mov_b32_e32 v79, v0
	v_mov_b32_e32 v84, v0
	v_mov_b32_e32 v85, v0
	v_mov_b32_e32 v86, v0
	v_mov_b32_e32 v87, v0
	v_mov_b32_e32 v92, v0
	v_mov_b32_e32 v93, v0
	v_mov_b32_e32 v94, v0
	v_mov_b32_e32 v95, v0
	v_mov_b32_e32 v100, v0
	v_mov_b32_e32 v101, v0
	v_mov_b32_e32 v102, v0
	v_mov_b32_e32 v103, v0
	v_mov_b32_e32 v108, v0
	v_mov_b32_e32 v109, v0
	v_mov_b32_e32 v110, v0
	v_mov_b32_e32 v111, v0
	v_mov_b32_e32 v80, v0
	v_mov_b32_e32 v81, v0
	v_mov_b32_e32 v82, v0
	v_mov_b32_e32 v83, v0
	v_mov_b32_e32 v88, v0
	v_mov_b32_e32 v89, v0
	v_mov_b32_e32 v90, v0
	v_mov_b32_e32 v91, v0
	v_mov_b32_e32 v96, v0
	v_mov_b32_e32 v97, v0
	v_mov_b32_e32 v98, v0
	v_mov_b32_e32 v99, v0
	v_mov_b32_e32 v104, v0
	v_mov_b32_e32 v105, v0
	v_mov_b32_e32 v106, v0
	v_mov_b32_e32 v107, v0
	v_mov_b32_e32 v112, v0
	v_mov_b32_e32 v113, v0
	v_mov_b32_e32 v114, v0
	v_mov_b32_e32 v115, v0
	v_mov_b32_e32 v116, v0
	v_mov_b32_e32 v117, v0
	v_mov_b32_e32 v118, v0
	v_mov_b32_e32 v119, v0
	v_mov_b32_e32 v120, v0
	v_mov_b32_e32 v121, v0
	v_mov_b32_e32 v122, v0
	v_mov_b32_e32 v123, v0
	v_mov_b32_e32 v124, v0
	v_mov_b32_e32 v125, v0
	v_mov_b32_e32 v126, v0
	v_mov_b32_e32 v127, v0
	s_cmp_lg_u32 s62, 0
	s_cbranch_scc1 .Lprio599_skip
	s_setprio 1

; #define PG8_STAGE(bufoff, gbase, voff) do { _Pragma("unroll") for (int _i = 0; _i < 2; ++_i) \
;         __builtin_amdgcn_global_load_lds((const unsigned*)((const char*)(gbase) + (voff)[_i]), (LAS unsigned*)(lds + (bufoff) + ldsw + _i * 8192), 16, 0, 0); } while (0)
; #define PG8_LDA(dst, b, h) do { _Pragma("unroll") for (int m = 0; m < 4; ++m) _Pragma("unroll") for (int k = 0; k < 2; ++k) dst[m][k] = *(const LAS bf16x8*)(lds + PG8_SA(b, h) + aoff + m * 2048 + k * 1024); } while (0)
; #define PG8_LDB(dst, b, h) do { _Pragma("unroll") for (int n = 0; n < 2; ++n) _Pragma("unroll") for (int k = 0; k < 2; ++k) dst[n][k] = *(const LAS bf16x8*)(lds + PG8_SB(b, h) + boff + n * 2048 + k * 1024); } while (0)
; #define PG8_MMA(ai, bj, At, Bt) do { __builtin_amdgcn_s_setprio(1); _Pragma("unroll") for (int m = 0; m < 4; ++m) _Pragma("unroll") for (int n = 0; n < 2; ++n) _Pragma("unroll") for (int k = 0; k < 2; ++k) \
;         acc[ai][bj][m][n] = __builtin_amdgcn_mfma_f32_16x16x32_bf16(Bt[n][k], At[m][k], acc[ai][bj][m][n], 0, 0, 0); __builtin_amdgcn_s_setprio(0); } while (0)
; #define PG8_WAIT_V(n) asm volatile("s_waitcnt vmcnt(" #n ")" ::: "memory")
; #define PG8_WAIT_L(n) asm volatile("s_waitcnt lgkmcnt(" #n ")" ::: "memory")
; #define PG8_BAR __builtin_amdgcn_s_barrier()
; #define PG8_SCHED __builtin_amdgcn_sched_barrier(0)
; template <class Epi, class Sched>
; __device__ __forceinline__ void gemm_phase(LAS unsigned char* lds, const Gemm g, const Sched& S, const Epi& E) {
;     ...
;         for (int t = 0; t < nt; t += 2) {
;             const bool last = (t == nt - 2);
;             const char* a1 = cA + (size_t)(t + 1) * kstep;
;             const char* a2 = last ? nA : cA + (size_t)(t + 2) * kstep; const char* b2 = last ? nB : cB + (size_t)(t + 2) * kstep;
;             const char* a3 = a2 + kstep; const char* b3 = b2 + kstep;
;             PG8_LDB(B0, 0, 0); PG8_LDB(B1, 0, 1); PG8_SCHED; PG8_LDA(At, 0, 0); PG8_STAGE(PG8_SA(1, 1), a1 + hstep, voffA);
;             PG8_WAIT_V(8); PG8_WAIT_L(0); PG8_BAR; PG8_MMA(0, 0, At, B0); PG8_MMA(0, 1, At, B1); PG8_BAR; PG8_SCHED;
;             PG8_LDA(At, 0, 1); PG8_STAGE(PG8_SB(0, 0), b2, voffB); PG8_STAGE(PG8_SB(0, 1), b2 + hstep, voffB); PG8_STAGE(PG8_SA(0, 0), a2, voffA);
.LBB0_599:
	s_add_i32 s19, s17, 2
	s_add_u32 s14, s6, 0x80
	s_addc_u32 s15, s7, 0
	s_add_i32 s33, 0, 0x10000
	s_cmp_eq_u32 s12, s17
	s_cselect_b32 s15, s1, s15
	s_cselect_b32 s14, s0, s14
	s_cselect_b32 s43, s65, s16
	s_cselect_b32 s42, s64, s13
	s_add_i32 s17, 0, 0x14000
	v_add_u32_e32 v140, s33, v231
	v_add_u32_e32 v156, s17, v231
	s_waitcnt lgkmcnt(0)
	ds_read_b128 v[128:131], v140
	ds_read_b128 v[132:135], v140 offset:1024
	ds_read_b128 v[136:139], v140 offset:2048
	ds_read_b128 v[140:143], v140 offset:3072
	ds_read_b128 v[144:147], v156
	ds_read_b128 v[148:151], v156 offset:1024
	ds_read_b128 v[152:155], v156 offset:2048
	ds_read_b128 v[156:159], v156 offset:3072
	v_lshl_add_u64 v[214:215], s[6:7], 0, v[198:199]
	s_add_i32 m0, s29, 0xc000
	ds_read_b128 v[160:163], v232
	ds_read_b128 v[164:167], v232 offset:1024
	ds_read_b128 v[168:171], v232 offset:2048
	ds_read_b128 v[172:175], v232 offset:3072
	ds_read_b128 v[176:179], v232 offset:4096
	ds_read_b128 v[202:205], v232 offset:5120
	ds_read_b128 v[206:209], v232 offset:6144
	ds_read_b128 v[210:213], v232 offset:7168
	global_load_lds_dwordx4 v[214:215], off
	v_lshl_add_u64 v[214:215], s[6:7], 0, v[200:201]
	s_add_i32 m0, s29, 0xe000
	s_nop 0
	global_load_lds_dwordx4 v[214:215], off
	s_waitcnt vmcnt(8)
	s_waitcnt lgkmcnt(0)
	s_barrier
	s_waitcnt lgkmcnt(0)
	v_mfma_f32_16x16x32_bf16 v[124:127], v[128:131], v[160:163], v[124:127]
	v_mfma_f32_16x16x32_bf16 v[120:123], v[136:139], v[160:163], v[120:123]
	v_mfma_f32_16x16x32_bf16 v[116:119], v[128:131], v[168:171], v[116:119]
	v_mfma_f32_16x16x32_bf16 v[112:115], v[136:139], v[168:171], v[112:115]
	v_mfma_f32_16x16x32_bf16 v[104:107], v[128:131], v[176:179], v[104:107]
	v_mfma_f32_16x16x32_bf16 v[96:99], v[136:139], v[176:179], v[96:99]
	v_mfma_f32_16x16x32_bf16 v[88:91], v[128:131], v[206:209], v[88:91]
	v_mfma_f32_16x16x32_bf16 v[80:83], v[136:139], v[206:209], v[80:83]
	v_mfma_f32_16x16x32_bf16 v[124:127], v[132:135], v[164:167], v[124:127]
	v_mfma_f32_16x16x32_bf16 v[120:123], v[140:143], v[164:167], v[120:123]
	v_mfma_f32_16x16x32_bf16 v[116:119], v[132:135], v[172:175], v[116:119]
	v_mfma_f32_16x16x32_bf16 v[112:115], v[140:143], v[172:175], v[112:115]
	v_mfma_f32_16x16x32_bf16 v[104:107], v[132:135], v[202:205], v[104:107]
	v_mfma_f32_16x16x32_bf16 v[96:99], v[140:143], v[202:205], v[96:99]
	v_mfma_f32_16x16x32_bf16 v[88:91], v[132:135], v[210:213], v[88:91]
	v_mfma_f32_16x16x32_bf16 v[80:83], v[140:143], v[210:213], v[80:83]
	v_mfma_f32_16x16x32_bf16 v[108:111], v[144:147], v[160:163], v[108:111]
	v_mfma_f32_16x16x32_bf16 v[100:103], v[152:155], v[160:163], v[100:103]
	v_mfma_f32_16x16x32_bf16 v[92:95], v[144:147], v[168:171], v[92:95]
	v_mfma_f32_16x16x32_bf16 v[84:87], v[152:155], v[168:171], v[84:87]
	v_mfma_f32_16x16x32_bf16 v[76:79], v[144:147], v[176:179], v[76:79]
	v_mfma_f32_16x16x32_bf16 v[72:75], v[152:155], v[176:179], v[72:75]
	v_mfma_f32_16x16x32_bf16 v[68:71], v[144:147], v[206:209], v[68:71]
	v_mfma_f32_16x16x32_bf16 v[64:67], v[152:155], v[206:209], v[64:67]
	v_mfma_f32_16x16x32_bf16 v[108:111], v[148:151], v[164:167], v[108:111]
	v_mfma_f32_16x16x32_bf16 v[100:103], v[156:159], v[164:167], v[100:103]
	v_mfma_f32_16x16x32_bf16 v[92:95], v[148:151], v[172:175], v[92:95]
	v_mfma_f32_16x16x32_bf16 v[84:87], v[156:159], v[172:175], v[84:87]
	v_mfma_f32_16x16x32_bf16 v[76:79], v[148:151], v[202:205], v[76:79]
	v_mfma_f32_16x16x32_bf16 v[72:75], v[156:159], v[202:205], v[72:75]
	v_mfma_f32_16x16x32_bf16 v[68:71], v[148:151], v[210:213], v[68:71]
	v_mfma_f32_16x16x32_bf16 v[64:67], v[156:159], v[210:213], v[64:67]
	s_barrier
	s_add_i32 s33, s33, s28
	v_lshl_add_u64 v[214:215], s[42:43], 0, v[184:185]
	s_mov_b32 m0, s33
	ds_read_b128 v[160:163], v232 offset:16384
	ds_read_b128 v[164:167], v232 offset:17408
	ds_read_b128 v[168:171], v232 offset:18432
	ds_read_b128 v[172:175], v232 offset:19456
	ds_read_b128 v[176:179], v232 offset:20480
	ds_read_b128 v[202:205], v232 offset:21504
	ds_read_b128 v[206:209], v232 offset:22528
	ds_read_b128 v[210:213], v232 offset:23552
	global_load_lds_dwordx4 v[214:215], off
	s_add_i32 m0, s33, 0x2000
	v_lshl_add_u64 v[216:217], s[42:43], 0, v[196:197]
	s_add_u32 s42, s42, s54
	s_addc_u32 s43, s43, 0
	s_add_i32 s17, s17, s28
	global_load_lds_dwordx4 v[216:217], off
	v_lshl_add_u64 v[234:235], s[42:43], 0, v[184:185]
	s_mov_b32 m0, s17
	v_lshl_add_u64 v[236:237], s[42:43], 0, v[196:197]
	global_load_lds_dwordx4 v[234:235], off
	s_add_i32 m0, s17, 0x2000
	v_lshl_add_u64 v[238:239], s[14:15], 0, v[192:193]
	global_load_lds_dwordx4 v[236:237], off
	s_mov_b32 m0, s29
	v_lshl_add_u64 v[240:241], s[14:15], 0, v[194:195]
	global_load_lds_dwordx4 v[238:239], off
	s_mov_b32 m0, s30
	s_nop 0
	global_load_lds_dwordx4 v[240:241], off
	s_waitcnt vmcnt(8)
	s_waitcnt lgkmcnt(0)
	s_barrier
; #define PG8_STAGE(bufoff, gbase, voff) do { _Pragma("unroll") for (int _i = 0; _i < 2; ++_i) \
;         __builtin_amdgcn_global_load_lds((const unsigned*)((const char*)(gbase) + (voff)[_i]), (LAS unsigned*)(lds + (bufoff) + ldsw + _i * 8192), 16, 0, 0); } while (0)
; #define PG8_LDA(dst, b, h) do { _Pragma("unroll") for (int m = 0; m < 4; ++m) _Pragma("unroll") for (int k = 0; k < 2; ++k) dst[m][k] = *(const LAS bf16x8*)(lds + PG8_SA(b, h) + aoff + m * 2048 + k * 1024); } while (0)
; #define PG8_LDB(dst, b, h) do { _Pragma("unroll") for (int n = 0; n < 2; ++n) _Pragma("unroll") for (int k = 0; k < 2; ++k) dst[n][k] = *(const LAS bf16x8*)(lds + PG8_SB(b, h) + boff + n * 2048 + k * 1024); } while (0)
; #define PG8_MMA(ai, bj, At, Bt) do { __builtin_amdgcn_s_setprio(1); _Pragma("unroll") for (int m = 0; m < 4; ++m) _Pragma("unroll") for (int n = 0; n < 2; ++n) _Pragma("unroll") for (int k = 0; k < 2; ++k) \
;         acc[ai][bj][m][n] = __builtin_amdgcn_mfma_f32_16x16x32_bf16(Bt[n][k], At[m][k], acc[ai][bj][m][n], 0, 0, 0); __builtin_amdgcn_s_setprio(0); } while (0)
; #define PG8_WAIT_V(n) asm volatile("s_waitcnt vmcnt(" #n ")" ::: "memory")
; #define PG8_WAIT_L(n) asm volatile("s_waitcnt lgkmcnt(" #n ")" ::: "memory")
; #define PG8_BAR __builtin_amdgcn_s_barrier()
; #define PG8_SCHED __builtin_amdgcn_sched_barrier(0)
; template <class Epi, class Sched>
; __device__ __forceinline__ void gemm_phase(LAS unsigned char* lds, const Gemm g, const Sched& S, const Epi& E) {
;     ...
;             PG8_WAIT_V(8); PG8_WAIT_L(0); PG8_BAR; PG8_MMA(1, 0, At, B0); PG8_MMA(1, 1, At, B1); PG8_BAR; PG8_SCHED;
;             PG8_LDB(B0, 1, 0); PG8_LDB(B1, 1, 1); PG8_SCHED; PG8_LDA(At, 1, 0); PG8_STAGE(PG8_SA(0, 1), a2 + hstep, voffA);
;             PG8_WAIT_V(8); PG8_WAIT_L(0); PG8_BAR; PG8_MMA(0, 0, At, B0); PG8_MMA(0, 1, At, B1); PG8_BAR; PG8_SCHED;
	s_waitcnt lgkmcnt(0)
	v_mfma_f32_16x16x32_bf16 v[60:63], v[128:131], v[160:163], v[60:63]
	v_mfma_f32_16x16x32_bf16 v[56:59], v[136:139], v[160:163], v[56:59]
	v_mfma_f32_16x16x32_bf16 v[52:55], v[128:131], v[168:171], v[52:55]
	v_mfma_f32_16x16x32_bf16 v[48:51], v[136:139], v[168:171], v[48:51]
	v_mfma_f32_16x16x32_bf16 v[36:39], v[128:131], v[176:179], v[36:39]
	v_mfma_f32_16x16x32_bf16 v[32:35], v[136:139], v[176:179], v[32:35]
	v_mfma_f32_16x16x32_bf16 v[20:23], v[128:131], v[206:209], v[20:23]
	v_mfma_f32_16x16x32_bf16 v[16:19], v[136:139], v[206:209], v[16:19]
	v_mfma_f32_16x16x32_bf16 v[60:63], v[132:135], v[164:167], v[60:63]
	v_mfma_f32_16x16x32_bf16 v[56:59], v[140:143], v[164:167], v[56:59]
	v_mfma_f32_16x16x32_bf16 v[52:55], v[132:135], v[172:175], v[52:55]
	v_mfma_f32_16x16x32_bf16 v[48:51], v[140:143], v[172:175], v[48:51]
	v_mfma_f32_16x16x32_bf16 v[36:39], v[132:135], v[202:205], v[36:39]
	v_mfma_f32_16x16x32_bf16 v[32:35], v[140:143], v[202:205], v[32:35]
	v_mfma_f32_16x16x32_bf16 v[20:23], v[132:135], v[210:213], v[20:23]
	v_mfma_f32_16x16x32_bf16 v[16:19], v[140:143], v[210:213], v[16:19]
	v_mfma_f32_16x16x32_bf16 v[44:47], v[144:147], v[160:163], v[44:47]
	v_mfma_f32_16x16x32_bf16 v[40:43], v[152:155], v[160:163], v[40:43]
	v_mfma_f32_16x16x32_bf16 v[28:31], v[144:147], v[168:171], v[28:31]
	v_mfma_f32_16x16x32_bf16 v[24:27], v[152:155], v[168:171], v[24:27]
	v_mfma_f32_16x16x32_bf16 v[12:15], v[144:147], v[176:179], v[12:15]
	v_mfma_f32_16x16x32_bf16 v[8:11], v[152:155], v[176:179], v[8:11]
	v_mfma_f32_16x16x32_bf16 v[4:7], v[144:147], v[206:209], v[4:7]
	v_mfma_f32_16x16x32_bf16 v[0:3], v[152:155], v[206:209], v[0:3]
	v_mfma_f32_16x16x32_bf16 v[44:47], v[148:151], v[164:167], v[44:47]
	v_mfma_f32_16x16x32_bf16 v[40:43], v[156:159], v[164:167], v[40:43]
	v_mfma_f32_16x16x32_bf16 v[28:31], v[148:151], v[172:175], v[28:31]
	v_mfma_f32_16x16x32_bf16 v[24:27], v[156:159], v[172:175], v[24:27]
	v_mfma_f32_16x16x32_bf16 v[12:15], v[148:151], v[202:205], v[12:15]
	v_mfma_f32_16x16x32_bf16 v[8:11], v[156:159], v[202:205], v[8:11]
	v_mfma_f32_16x16x32_bf16 v[4:7], v[148:151], v[210:213], v[4:7]
	v_mfma_f32_16x16x32_bf16 v[0:3], v[156:159], v[210:213], v[0:3]
	s_barrier
	s_add_i32 s17, 0, 0x18000
	s_add_i32 s33, 0, 0x1c000
	v_add_u32_e32 v140, s17, v231
	v_add_u32_e32 v156, s33, v231
	ds_read_b128 v[128:131], v140
	ds_read_b128 v[132:135], v140 offset:1024
	ds_read_b128 v[136:139], v140 offset:2048
	ds_read_b128 v[140:143], v140 offset:3072
	ds_read_b128 v[144:147], v156
	ds_read_b128 v[148:151], v156 offset:1024
	ds_read_b128 v[152:155], v156 offset:2048
	ds_read_b128 v[156:159], v156 offset:3072
	s_add_u32 s14, s14, s54
	s_addc_u32 s15, s15, 0
	s_mov_b32 m0, s31
	v_lshl_add_u64 v[242:243], s[14:15], 0, v[192:193]
	ds_read_b128 v[160:163], v232 offset:32768
	ds_read_b128 v[164:167], v232 offset:33792
	ds_read_b128 v[168:171], v232 offset:34816
	ds_read_b128 v[172:175], v232 offset:35840
	ds_read_b128 v[176:179], v232 offset:36864
	ds_read_b128 v[202:205], v232 offset:37888
	ds_read_b128 v[206:209], v232 offset:38912
	ds_read_b128 v[210:213], v232 offset:39936
	global_load_lds_dwordx4 v[242:243], off
	v_lshl_add_u64 v[242:243], s[14:15], 0, v[194:195]
	s_mov_b32 m0, s34
	s_nop 0
	global_load_lds_dwordx4 v[242:243], off
	s_waitcnt vmcnt(8)
	s_waitcnt lgkmcnt(0)
	s_barrier
	s_waitcnt lgkmcnt(0)
	v_mfma_f32_16x16x32_bf16 v[124:127], v[128:131], v[160:163], v[124:127]
	v_mfma_f32_16x16x32_bf16 v[120:123], v[136:139], v[160:163], v[120:123]
	v_mfma_f32_16x16x32_bf16 v[116:119], v[128:131], v[168:171], v[116:119]
	v_mfma_f32_16x16x32_bf16 v[112:115], v[136:139], v[168:171], v[112:115]
	v_mfma_f32_16x16x32_bf16 v[104:107], v[128:131], v[176:179], v[104:107]
	v_mfma_f32_16x16x32_bf16 v[96:99], v[136:139], v[176:179], v[96:99]
	v_mfma_f32_16x16x32_bf16 v[88:91], v[128:131], v[206:209], v[88:91]
	v_mfma_f32_16x16x32_bf16 v[80:83], v[136:139], v[206:209], v[80:83]
	v_mfma_f32_16x16x32_bf16 v[124:127], v[132:135], v[164:167], v[124:127]
	v_mfma_f32_16x16x32_bf16 v[120:123], v[140:143], v[164:167], v[120:123]
	v_mfma_f32_16x16x32_bf16 v[116:119], v[132:135], v[172:175], v[116:119]
	v_mfma_f32_16x16x32_bf16 v[112:115], v[140:143], v[172:175], v[112:115]
	v_mfma_f32_16x16x32_bf16 v[104:107], v[132:135], v[202:205], v[104:107]
	v_mfma_f32_16x16x32_bf16 v[96:99], v[140:143], v[202:205], v[96:99]
	v_mfma_f32_16x16x32_bf16 v[88:91], v[132:135], v[210:213], v[88:91]
	v_mfma_f32_16x16x32_bf16 v[80:83], v[140:143], v[210:213], v[80:83]
	v_mfma_f32_16x16x32_bf16 v[108:111], v[144:147], v[160:163], v[108:111]
	v_mfma_f32_16x16x32_bf16 v[100:103], v[152:155], v[160:163], v[100:103]
	v_mfma_f32_16x16x32_bf16 v[92:95], v[144:147], v[168:171], v[92:95]
	v_mfma_f32_16x16x32_bf16 v[84:87], v[152:155], v[168:171], v[84:87]
	v_mfma_f32_16x16x32_bf16 v[76:79], v[144:147], v[176:179], v[76:79]
	v_mfma_f32_16x16x32_bf16 v[72:75], v[152:155], v[176:179], v[72:75]
	v_mfma_f32_16x16x32_bf16 v[68:71], v[144:147], v[206:209], v[68:71]
	v_mfma_f32_16x16x32_bf16 v[64:67], v[152:155], v[206:209], v[64:67]
	v_mfma_f32_16x16x32_bf16 v[108:111], v[148:151], v[164:167], v[108:111]
	v_mfma_f32_16x16x32_bf16 v[100:103], v[156:159], v[164:167], v[100:103]
	v_mfma_f32_16x16x32_bf16 v[92:95], v[148:151], v[172:175], v[92:95]
	v_mfma_f32_16x16x32_bf16 v[84:87], v[156:159], v[172:175], v[84:87]
	v_mfma_f32_16x16x32_bf16 v[76:79], v[148:151], v[202:205], v[76:79]
	v_mfma_f32_16x16x32_bf16 v[72:75], v[156:159], v[202:205], v[72:75]
	v_mfma_f32_16x16x32_bf16 v[68:71], v[148:151], v[210:213], v[68:71]
	v_mfma_f32_16x16x32_bf16 v[64:67], v[156:159], v[210:213], v[64:67]
	s_barrier
; #define PG8_STAGE(bufoff, gbase, voff) do { _Pragma("unroll") for (int _i = 0; _i < 2; ++_i) \
;         __builtin_amdgcn_global_load_lds((const unsigned*)((const char*)(gbase) + (voff)[_i]), (LAS unsigned*)(lds + (bufoff) + ldsw + _i * 8192), 16, 0, 0); } while (0)
; #define PG8_LDA(dst, b, h) do { _Pragma("unroll") for (int m = 0; m < 4; ++m) _Pragma("unroll") for (int k = 0; k < 2; ++k) dst[m][k] = *(const LAS bf16x8*)(lds + PG8_SA(b, h) + aoff + m * 2048 + k * 1024); } while (0)
; #define PG8_MMA(ai, bj, At, Bt) do { __builtin_amdgcn_s_setprio(1); _Pragma("unroll") for (int m = 0; m < 4; ++m) _Pragma("unroll") for (int n = 0; n < 2; ++n) _Pragma("unroll") for (int k = 0; k < 2; ++k) \
;         acc[ai][bj][m][n] = __builtin_amdgcn_mfma_f32_16x16x32_bf16(Bt[n][k], At[m][k], acc[ai][bj][m][n], 0, 0, 0); __builtin_amdgcn_s_setprio(0); } while (0)
; #define PG8_WAIT_V(n) asm volatile("s_waitcnt vmcnt(" #n ")" ::: "memory")
; #define PG8_WAIT_L(n) asm volatile("s_waitcnt lgkmcnt(" #n ")" ::: "memory")
; #define PG8_BAR __builtin_amdgcn_s_barrier()
; #define PG8_SCHED __builtin_amdgcn_sched_barrier(0)
; template <class Epi, class Sched>
; __device__ __forceinline__ void gemm_phase(LAS unsigned char* lds, const Gemm g, const Sched& S, const Epi& E) {
;     ...
;             PG8_LDA(At, 1, 1); PG8_STAGE(PG8_SB(1, 0), b3, voffB); PG8_STAGE(PG8_SB(1, 1), b3 + hstep, voffB); PG8_STAGE(PG8_SA(1, 0), a3, voffA);
;             PG8_WAIT_V(8); PG8_WAIT_L(0); PG8_BAR; PG8_MMA(1, 0, At, B0); PG8_MMA(1, 1, At, B1); PG8_BAR; PG8_SCHED;
;         }
;         if (wr == 0) PG8_BAR;
	s_add_i32 s14, s17, s28
	v_lshl_add_u64 v[214:215], v[214:215], 0, s[84:85]
	s_mov_b32 m0, s14
	ds_read_b128 v[160:163], v232 offset:49152
	ds_read_b128 v[164:167], v232 offset:50176
	ds_read_b128 v[168:171], v232 offset:51200
	ds_read_b128 v[172:175], v232 offset:52224
	ds_read_b128 v[176:179], v232 offset:53248
	ds_read_b128 v[202:205], v232 offset:54272
	ds_read_b128 v[206:209], v232 offset:55296
	ds_read_b128 v[210:213], v232 offset:56320
	global_load_lds_dwordx4 v[214:215], off
	v_lshl_add_u64 v[214:215], v[216:217], 0, s[84:85]
	s_add_i32 m0, s14, 0x2000
	s_add_i32 s14, s33, s28
	global_load_lds_dwordx4 v[214:215], off
	v_lshl_add_u64 v[214:215], v[234:235], 0, s[84:85]
	s_mov_b32 m0, s14
	s_nop 0
	global_load_lds_dwordx4 v[214:215], off
	v_lshl_add_u64 v[214:215], v[236:237], 0, s[84:85]
	s_add_i32 m0, s14, 0x2000
	s_nop 0
	global_load_lds_dwordx4 v[214:215], off
	v_lshl_add_u64 v[214:215], v[238:239], 0, s[84:85]
	s_mov_b32 m0, s66
	s_nop 0
	global_load_lds_dwordx4 v[214:215], off
	v_lshl_add_u64 v[214:215], v[240:241], 0, s[84:85]
	s_mov_b32 m0, s67
	s_nop 0
	global_load_lds_dwordx4 v[214:215], off
	s_waitcnt vmcnt(8)
	s_waitcnt lgkmcnt(0)
	s_barrier
	s_waitcnt lgkmcnt(0)
	v_mfma_f32_16x16x32_bf16 v[60:63], v[128:131], v[160:163], v[60:63]
	v_mfma_f32_16x16x32_bf16 v[56:59], v[136:139], v[160:163], v[56:59]
	v_mfma_f32_16x16x32_bf16 v[52:55], v[128:131], v[168:171], v[52:55]
	v_mfma_f32_16x16x32_bf16 v[48:51], v[136:139], v[168:171], v[48:51]
	v_mfma_f32_16x16x32_bf16 v[36:39], v[128:131], v[176:179], v[36:39]
	v_mfma_f32_16x16x32_bf16 v[32:35], v[136:139], v[176:179], v[32:35]
	v_mfma_f32_16x16x32_bf16 v[20:23], v[128:131], v[206:209], v[20:23]
	v_mfma_f32_16x16x32_bf16 v[16:19], v[136:139], v[206:209], v[16:19]
	v_mfma_f32_16x16x32_bf16 v[60:63], v[132:135], v[164:167], v[60:63]
	v_mfma_f32_16x16x32_bf16 v[56:59], v[140:143], v[164:167], v[56:59]
	v_mfma_f32_16x16x32_bf16 v[52:55], v[132:135], v[172:175], v[52:55]
	v_mfma_f32_16x16x32_bf16 v[48:51], v[140:143], v[172:175], v[48:51]
	v_mfma_f32_16x16x32_bf16 v[36:39], v[132:135], v[202:205], v[36:39]
	v_mfma_f32_16x16x32_bf16 v[32:35], v[140:143], v[202:205], v[32:35]
	v_mfma_f32_16x16x32_bf16 v[20:23], v[132:135], v[210:213], v[20:23]
	v_mfma_f32_16x16x32_bf16 v[16:19], v[140:143], v[210:213], v[16:19]
	v_mfma_f32_16x16x32_bf16 v[44:47], v[144:147], v[160:163], v[44:47]
	v_mfma_f32_16x16x32_bf16 v[40:43], v[152:155], v[160:163], v[40:43]
	v_mfma_f32_16x16x32_bf16 v[28:31], v[144:147], v[168:171], v[28:31]
	v_mfma_f32_16x16x32_bf16 v[24:27], v[152:155], v[168:171], v[24:27]
	v_mfma_f32_16x16x32_bf16 v[12:15], v[144:147], v[176:179], v[12:15]
	v_mfma_f32_16x16x32_bf16 v[8:11], v[152:155], v[176:179], v[8:11]
	v_mfma_f32_16x16x32_bf16 v[4:7], v[144:147], v[206:209], v[4:7]
	v_mfma_f32_16x16x32_bf16 v[0:3], v[152:155], v[206:209], v[0:3]
	v_mfma_f32_16x16x32_bf16 v[44:47], v[148:151], v[164:167], v[44:47]
	v_mfma_f32_16x16x32_bf16 v[40:43], v[156:159], v[164:167], v[40:43]
	v_mfma_f32_16x16x32_bf16 v[28:31], v[148:151], v[172:175], v[28:31]
	v_mfma_f32_16x16x32_bf16 v[24:27], v[156:159], v[172:175], v[24:27]
	v_mfma_f32_16x16x32_bf16 v[12:15], v[148:151], v[202:205], v[12:15]
	v_mfma_f32_16x16x32_bf16 v[8:11], v[156:159], v[202:205], v[8:11]
	v_mfma_f32_16x16x32_bf16 v[4:7], v[148:151], v[210:213], v[4:7]
	v_mfma_f32_16x16x32_bf16 v[0:3], v[156:159], v[210:213], v[0:3]
	s_barrier
	s_add_u32 s6, s6, 0x100
	s_addc_u32 s7, s7, 0
	s_add_u32 s13, s13, 0x100
	s_addc_u32 s16, s16, 0
	s_cmp_ge_u32 s19, s8
	s_mov_b32 s17, s19
	s_cbranch_scc0 .LBB0_599
	s_setprio 0
	s_and_b64 vcc, exec, s[62:63]
	s_cbranch_vccz .LBB0_602
	s_barrier

; template <class Epi, class Sched>
; __device__ __forceinline__ void gemm_phase(LAS unsigned char* lds, const Gemm g, const Sched& S, const Epi& E) {
;     ...
;         const char* nA = has_next ? (const char*)g.A + (size_t)nxt.pm * tstep + nko : cA; const char* nB = has_next ? (const char*)g.Bt + (size_t)nxt.pn * tstep + nko : cB;
;     ...
;         for (int a = 0; a < 2; ++a)
; #pragma unroll
;             for (int b = 0; b < 2; ++b)
; #pragma unroll
;                 for (int m = 0; m < 4; ++m)
; #pragma unroll
;                     for (int n = 0; n < 2; ++n) acc[a][b][m][n] = (f32x4){0.f, 0.f, 0.f, 0.f};
.LBB0_743:
	s_ashr_i32 s15, s14, 31
	s_lshl_b64 s[18:19], s[14:15], 19
	s_add_u32 s18, s92, s18
	s_addc_u32 s19, s93, s19
	s_and_b64 s[20:21], s[38:39], exec
	s_cselect_b32 s15, s19, s23
	s_cselect_b32 s44, s18, s22
	s_ashr_i32 s17, s16, 31
	s_lshl_b64 s[20:21], s[16:17], 19
	s_add_u32 s20, s9, s20
	s_addc_u32 s21, s12, s21
	s_and_b64 s[26:27], s[38:39], exec
	s_cselect_b32 s17, s21, s25
	s_cselect_b32 s45, s20, s24
	s_add_u32 s22, s22, 0x40080
	s_addc_u32 s23, s23, 0
	s_add_u32 s46, s24, 0x100
	v_mov_b32_e32 v4, 0
	s_addc_u32 s47, s25, 0
	s_mov_b32 s48, -2
	v_mov_b32_e32 v5, v4
	v_mov_b32_e32 v6, v4
	v_mov_b32_e32 v7, v4
	v_mov_b32_e32 v0, v4
	v_mov_b32_e32 v1, v4
	v_mov_b32_e32 v2, v4
	v_mov_b32_e32 v3, v4
	v_mov_b32_e32 v20, v4
	v_mov_b32_e32 v21, v4
	v_mov_b32_e32 v22, v4
	v_mov_b32_e32 v23, v4
	v_mov_b32_e32 v16, v4
	v_mov_b32_e32 v17, v4
	v_mov_b32_e32 v18, v4
	v_mov_b32_e32 v19, v4
	v_mov_b32_e32 v36, v4
	v_mov_b32_e32 v37, v4
	v_mov_b32_e32 v38, v4
	v_mov_b32_e32 v39, v4
	v_mov_b32_e32 v32, v4
	v_mov_b32_e32 v33, v4
	v_mov_b32_e32 v34, v4
	v_mov_b32_e32 v35, v4
	v_mov_b32_e32 v52, v4
	v_mov_b32_e32 v53, v4
	v_mov_b32_e32 v54, v4
	v_mov_b32_e32 v55, v4
	v_mov_b32_e32 v48, v4
	v_mov_b32_e32 v49, v4
	v_mov_b32_e32 v50, v4
	v_mov_b32_e32 v51, v4
	v_mov_b32_e32 v8, v4
	v_mov_b32_e32 v9, v4
	v_mov_b32_e32 v10, v4
	v_mov_b32_e32 v11, v4
	v_mov_b32_e32 v12, v4
	v_mov_b32_e32 v13, v4
	v_mov_b32_e32 v14, v4
	v_mov_b32_e32 v15, v4
	v_mov_b32_e32 v24, v4
	v_mov_b32_e32 v25, v4
	v_mov_b32_e32 v26, v4
	v_mov_b32_e32 v27, v4
	v_mov_b32_e32 v28, v4
	v_mov_b32_e32 v29, v4
	v_mov_b32_e32 v30, v4
	v_mov_b32_e32 v31, v4
	v_mov_b32_e32 v40, v4
	v_mov_b32_e32 v41, v4
	v_mov_b32_e32 v42, v4
	v_mov_b32_e32 v43, v4
	v_mov_b32_e32 v44, v4
	v_mov_b32_e32 v45, v4
	v_mov_b32_e32 v46, v4
	v_mov_b32_e32 v47, v4
	v_mov_b32_e32 v56, v4
	v_mov_b32_e32 v57, v4
	v_mov_b32_e32 v58, v4
	v_mov_b32_e32 v59, v4
	v_mov_b32_e32 v60, v4
	v_mov_b32_e32 v61, v4
	v_mov_b32_e32 v62, v4
	v_mov_b32_e32 v63, v4
	v_mov_b32_e32 v68, v4
	v_mov_b32_e32 v69, v4
	v_mov_b32_e32 v70, v4
	v_mov_b32_e32 v71, v4
	v_mov_b32_e32 v64, v4
	v_mov_b32_e32 v65, v4
	v_mov_b32_e32 v66, v4
	v_mov_b32_e32 v67, v4
	v_mov_b32_e32 v84, v4
	v_mov_b32_e32 v85, v4
	v_mov_b32_e32 v86, v4
	v_mov_b32_e32 v87, v4
	v_mov_b32_e32 v80, v4
	v_mov_b32_e32 v81, v4
	v_mov_b32_e32 v82, v4
	v_mov_b32_e32 v83, v4
	v_mov_b32_e32 v100, v4
	v_mov_b32_e32 v101, v4
	v_mov_b32_e32 v102, v4
	v_mov_b32_e32 v103, v4
	v_mov_b32_e32 v96, v4
	v_mov_b32_e32 v97, v4
	v_mov_b32_e32 v98, v4
	v_mov_b32_e32 v99, v4
	v_mov_b32_e32 v116, v4
	v_mov_b32_e32 v117, v4
	v_mov_b32_e32 v118, v4
	v_mov_b32_e32 v119, v4
	v_mov_b32_e32 v112, v4
	v_mov_b32_e32 v113, v4
	v_mov_b32_e32 v114, v4
	v_mov_b32_e32 v115, v4
	v_mov_b32_e32 v72, v4
	v_mov_b32_e32 v73, v4
	v_mov_b32_e32 v74, v4
	v_mov_b32_e32 v75, v4
	v_mov_b32_e32 v76, v4
	v_mov_b32_e32 v77, v4
	v_mov_b32_e32 v78, v4
	v_mov_b32_e32 v79, v4
	v_mov_b32_e32 v88, v4
	v_mov_b32_e32 v89, v4
	v_mov_b32_e32 v90, v4
	v_mov_b32_e32 v91, v4
	v_mov_b32_e32 v92, v4
	v_mov_b32_e32 v93, v4
	v_mov_b32_e32 v94, v4
	v_mov_b32_e32 v95, v4
	v_mov_b32_e32 v104, v4
	v_mov_b32_e32 v105, v4
	v_mov_b32_e32 v106, v4
	v_mov_b32_e32 v107, v4
	v_mov_b32_e32 v108, v4
	v_mov_b32_e32 v109, v4
	v_mov_b32_e32 v110, v4
	v_mov_b32_e32 v111, v4
	v_mov_b32_e32 v120, v4
	v_mov_b32_e32 v121, v4
	v_mov_b32_e32 v122, v4
	v_mov_b32_e32 v123, v4
	v_mov_b32_e32 v124, v4
	v_mov_b32_e32 v125, v4
	v_mov_b32_e32 v126, v4
	v_mov_b32_e32 v127, v4
	s_cmp_lg_u32 s6, 0
	s_cbranch_scc1 .Lprio744_skip
	s_setprio 1

; #define PG8_STAGE(bufoff, gbase, voff) do { _Pragma("unroll") for (int _i = 0; _i < 2; ++_i) \
;         __builtin_amdgcn_global_load_lds((const unsigned*)((const char*)(gbase) + (voff)[_i]), (LAS unsigned*)(lds + (bufoff) + ldsw + _i * 8192), 16, 0, 0); } while (0)
; #define PG8_LDA(dst, b, h) do { _Pragma("unroll") for (int m = 0; m < 4; ++m) _Pragma("unroll") for (int k = 0; k < 2; ++k) dst[m][k] = *(const LAS bf16x8*)(lds + PG8_SA(b, h) + aoff + m * 2048 + k * 1024); } while (0)
; #define PG8_LDB(dst, b, h) do { _Pragma("unroll") for (int n = 0; n < 2; ++n) _Pragma("unroll") for (int k = 0; k < 2; ++k) dst[n][k] = *(const LAS bf16x8*)(lds + PG8_SB(b, h) + boff + n * 2048 + k * 1024); } while (0)
; #define PG8_MMA(ai, bj, At, Bt) do { __builtin_amdgcn_s_setprio(1); _Pragma("unroll") for (int m = 0; m < 4; ++m) _Pragma("unroll") for (int n = 0; n < 2; ++n) _Pragma("unroll") for (int k = 0; k < 2; ++k) \
;         acc[ai][bj][m][n] = __builtin_amdgcn_mfma_f32_16x16x32_bf16(Bt[n][k], At[m][k], acc[ai][bj][m][n], 0, 0, 0); __builtin_amdgcn_s_setprio(0); } while (0)
; #define PG8_WAIT_V(n) asm volatile("s_waitcnt vmcnt(" #n ")" ::: "memory")
; #define PG8_WAIT_L(n) asm volatile("s_waitcnt lgkmcnt(" #n ")" ::: "memory")
; #define PG8_BAR __builtin_amdgcn_s_barrier()
; #define PG8_SCHED __builtin_amdgcn_sched_barrier(0)
; template <class Epi, class Sched>
; __device__ __forceinline__ void gemm_phase(LAS unsigned char* lds, const Gemm g, const Sched& S, const Epi& E) {
;     ...
;         for (int t = 0; t < nt; t += 2) {
;             const bool last = (t == nt - 2);
;             const char* a1 = cA + (size_t)(t + 1) * kstep;
;             const char* a2 = last ? nA : cA + (size_t)(t + 2) * kstep; const char* b2 = last ? nB : cB + (size_t)(t + 2) * kstep;
;             const char* a3 = a2 + kstep; const char* b3 = b2 + kstep;
;             PG8_LDB(B0, 0, 0); PG8_LDB(B1, 0, 1); PG8_SCHED; PG8_LDA(At, 0, 0); PG8_STAGE(PG8_SA(1, 1), a1 + hstep, voffA);
;             PG8_WAIT_V(8); PG8_WAIT_L(0); PG8_BAR; PG8_MMA(0, 0, At, B0); PG8_MMA(0, 1, At, B1); PG8_BAR; PG8_SCHED;
;             PG8_LDA(At, 0, 1); PG8_STAGE(PG8_SB(0, 0), b2, voffB); PG8_STAGE(PG8_SB(0, 1), b2 + hstep, voffB); PG8_STAGE(PG8_SA(0, 0), a2, voffA);
.LBB0_744:
	s_add_u32 s24, s22, 0xfffc0080
	s_addc_u32 s25, s23, -1
	s_add_i32 s49, 0, 0x10000
	s_cmp_eq_u32 s48, 12
	s_cselect_b32 s27, s15, s25
	s_cselect_b32 s26, s44, s24
	s_cselect_b32 s25, s17, s47
	s_cselect_b32 s24, s45, s46
	s_add_i32 s52, 0, 0x14000
	v_add_u32_e32 v140, s49, v162
	v_add_u32_e32 v158, s52, v162
	ds_read_b128 v[128:131], v140
	ds_read_b128 v[132:135], v140 offset:1024
	ds_read_b128 v[136:139], v140 offset:2048
	ds_read_b128 v[140:143], v140 offset:3072
	ds_read_b128 v[154:157], v158
	ds_read_b128 v[164:167], v158 offset:1024
	ds_read_b128 v[168:171], v158 offset:2048
	ds_read_b128 v[172:175], v158 offset:3072
	v_lshl_add_u64 v[158:159], s[22:23], 0, v[150:151]
	s_add_i32 m0, s28, 0xc000
	ds_read_b128 v[176:179], v163
	ds_read_b128 v[192:195], v163 offset:1024
	ds_read_b128 v[196:199], v163 offset:2048
	ds_read_b128 v[200:203], v163 offset:3072
	ds_read_b128 v[204:207], v163 offset:4096
	ds_read_b128 v[208:211], v163 offset:5120
	ds_read_b128 v[212:215], v163 offset:6144
	ds_read_b128 v[230:233], v163 offset:7168
	global_load_lds_dwordx4 v[158:159], off
	v_lshl_add_u64 v[158:159], s[22:23], 0, v[152:153]
	s_add_i32 m0, s28, 0xe000
	s_nop 0
	global_load_lds_dwordx4 v[158:159], off
	s_waitcnt vmcnt(8)
	s_waitcnt lgkmcnt(0)
	s_barrier
	s_waitcnt lgkmcnt(0)
	v_mfma_f32_16x16x32_bf16 v[124:127], v[128:131], v[176:179], v[124:127]
	v_mfma_f32_16x16x32_bf16 v[120:123], v[136:139], v[176:179], v[120:123]
	v_mfma_f32_16x16x32_bf16 v[108:111], v[128:131], v[196:199], v[108:111]
	v_mfma_f32_16x16x32_bf16 v[104:107], v[136:139], v[196:199], v[104:107]
	v_mfma_f32_16x16x32_bf16 v[92:95], v[128:131], v[204:207], v[92:95]
	v_mfma_f32_16x16x32_bf16 v[88:91], v[136:139], v[204:207], v[88:91]
	v_mfma_f32_16x16x32_bf16 v[76:79], v[128:131], v[212:215], v[76:79]
	v_mfma_f32_16x16x32_bf16 v[72:75], v[136:139], v[212:215], v[72:75]
	v_mfma_f32_16x16x32_bf16 v[124:127], v[132:135], v[192:195], v[124:127]
	v_mfma_f32_16x16x32_bf16 v[120:123], v[140:143], v[192:195], v[120:123]
	v_mfma_f32_16x16x32_bf16 v[108:111], v[132:135], v[200:203], v[108:111]
	v_mfma_f32_16x16x32_bf16 v[104:107], v[140:143], v[200:203], v[104:107]
	v_mfma_f32_16x16x32_bf16 v[92:95], v[132:135], v[208:211], v[92:95]
	v_mfma_f32_16x16x32_bf16 v[88:91], v[140:143], v[208:211], v[88:91]
	v_mfma_f32_16x16x32_bf16 v[76:79], v[132:135], v[230:233], v[76:79]
	v_mfma_f32_16x16x32_bf16 v[72:75], v[140:143], v[230:233], v[72:75]
	v_mfma_f32_16x16x32_bf16 v[112:115], v[154:157], v[176:179], v[112:115]
	v_mfma_f32_16x16x32_bf16 v[116:119], v[168:171], v[176:179], v[116:119]
	v_mfma_f32_16x16x32_bf16 v[96:99], v[154:157], v[196:199], v[96:99]
	v_mfma_f32_16x16x32_bf16 v[100:103], v[168:171], v[196:199], v[100:103]
	v_mfma_f32_16x16x32_bf16 v[80:83], v[154:157], v[204:207], v[80:83]
	v_mfma_f32_16x16x32_bf16 v[84:87], v[168:171], v[204:207], v[84:87]
	v_mfma_f32_16x16x32_bf16 v[64:67], v[154:157], v[212:215], v[64:67]
	v_mfma_f32_16x16x32_bf16 v[68:71], v[168:171], v[212:215], v[68:71]
	v_mfma_f32_16x16x32_bf16 v[112:115], v[164:167], v[192:195], v[112:115]
	v_mfma_f32_16x16x32_bf16 v[116:119], v[172:175], v[192:195], v[116:119]
	v_mfma_f32_16x16x32_bf16 v[96:99], v[164:167], v[200:203], v[96:99]
	v_mfma_f32_16x16x32_bf16 v[100:103], v[172:175], v[200:203], v[100:103]
	v_mfma_f32_16x16x32_bf16 v[80:83], v[164:167], v[208:211], v[80:83]
	v_mfma_f32_16x16x32_bf16 v[84:87], v[172:175], v[208:211], v[84:87]
	v_mfma_f32_16x16x32_bf16 v[64:67], v[164:167], v[230:233], v[64:67]
	v_mfma_f32_16x16x32_bf16 v[68:71], v[172:175], v[230:233], v[68:71]
	s_barrier
	s_add_i32 s49, s49, s8
	v_lshl_add_u64 v[158:159], s[24:25], 0, v[184:185]
	s_mov_b32 m0, s49
	ds_read_b128 v[176:179], v163 offset:16384
	ds_read_b128 v[192:195], v163 offset:17408
	ds_read_b128 v[196:199], v163 offset:18432
	ds_read_b128 v[200:203], v163 offset:19456
	ds_read_b128 v[204:207], v163 offset:20480
	ds_read_b128 v[208:211], v163 offset:21504
	ds_read_b128 v[212:215], v163 offset:22528
	ds_read_b128 v[230:233], v163 offset:23552
	global_load_lds_dwordx4 v[158:159], off
	s_add_i32 m0, s49, 0x2000
	s_add_u32 s50, s24, 0x40000
	v_lshl_add_u64 v[216:217], s[24:25], 0, v[144:145]
	s_addc_u32 s51, s25, 0
	s_add_i32 s49, s52, s8
	global_load_lds_dwordx4 v[216:217], off
	v_lshl_add_u64 v[234:235], s[50:51], 0, v[184:185]
	s_mov_b32 m0, s49
	v_lshl_add_u64 v[236:237], s[26:27], 0, v[146:147]
	global_load_lds_dwordx4 v[234:235], off
	v_lshl_add_u64 v[234:235], s[50:51], 0, v[144:145]
	s_add_i32 m0, s49, 0x2000
	s_nop 0
	global_load_lds_dwordx4 v[234:235], off
	v_lshl_add_u64 v[234:235], s[26:27], 0, v[148:149]
	s_mov_b32 m0, s28
	s_nop 0
	global_load_lds_dwordx4 v[234:235], off
	s_mov_b32 m0, s29
	s_nop 0
	global_load_lds_dwordx4 v[236:237], off
	s_waitcnt vmcnt(8)
	s_waitcnt lgkmcnt(0)
	s_barrier
; #define PG8_STAGE(bufoff, gbase, voff) do { _Pragma("unroll") for (int _i = 0; _i < 2; ++_i) \
;         __builtin_amdgcn_global_load_lds((const unsigned*)((const char*)(gbase) + (voff)[_i]), (LAS unsigned*)(lds + (bufoff) + ldsw + _i * 8192), 16, 0, 0); } while (0)
; #define PG8_LDA(dst, b, h) do { _Pragma("unroll") for (int m = 0; m < 4; ++m) _Pragma("unroll") for (int k = 0; k < 2; ++k) dst[m][k] = *(const LAS bf16x8*)(lds + PG8_SA(b, h) + aoff + m * 2048 + k * 1024); } while (0)
; #define PG8_LDB(dst, b, h) do { _Pragma("unroll") for (int n = 0; n < 2; ++n) _Pragma("unroll") for (int k = 0; k < 2; ++k) dst[n][k] = *(const LAS bf16x8*)(lds + PG8_SB(b, h) + boff + n * 2048 + k * 1024); } while (0)
; #define PG8_MMA(ai, bj, At, Bt) do { __builtin_amdgcn_s_setprio(1); _Pragma("unroll") for (int m = 0; m < 4; ++m) _Pragma("unroll") for (int n = 0; n < 2; ++n) _Pragma("unroll") for (int k = 0; k < 2; ++k) \
;         acc[ai][bj][m][n] = __builtin_amdgcn_mfma_f32_16x16x32_bf16(Bt[n][k], At[m][k], acc[ai][bj][m][n], 0, 0, 0); __builtin_amdgcn_s_setprio(0); } while (0)
; #define PG8_WAIT_V(n) asm volatile("s_waitcnt vmcnt(" #n ")" ::: "memory")
; #define PG8_WAIT_L(n) asm volatile("s_waitcnt lgkmcnt(" #n ")" ::: "memory")
; #define PG8_BAR __builtin_amdgcn_s_barrier()
; #define PG8_SCHED __builtin_amdgcn_sched_barrier(0)
; template <class Epi, class Sched>
; __device__ __forceinline__ void gemm_phase(LAS unsigned char* lds, const Gemm g, const Sched& S, const Epi& E) {
;     ...
;             PG8_WAIT_V(8); PG8_WAIT_L(0); PG8_BAR; PG8_MMA(1, 0, At, B0); PG8_MMA(1, 1, At, B1); PG8_BAR; PG8_SCHED;
;             PG8_LDB(B0, 1, 0); PG8_LDB(B1, 1, 1); PG8_SCHED; PG8_LDA(At, 1, 0); PG8_STAGE(PG8_SA(0, 1), a2 + hstep, voffA);
;             PG8_WAIT_V(8); PG8_WAIT_L(0); PG8_BAR; PG8_MMA(0, 0, At, B0); PG8_MMA(0, 1, At, B1); PG8_BAR; PG8_SCHED;
	s_waitcnt lgkmcnt(0)
	v_mfma_f32_16x16x32_bf16 v[60:63], v[128:131], v[176:179], v[60:63]
	v_mfma_f32_16x16x32_bf16 v[56:59], v[136:139], v[176:179], v[56:59]
	v_mfma_f32_16x16x32_bf16 v[44:47], v[128:131], v[196:199], v[44:47]
	v_mfma_f32_16x16x32_bf16 v[40:43], v[136:139], v[196:199], v[40:43]
	v_mfma_f32_16x16x32_bf16 v[28:31], v[128:131], v[204:207], v[28:31]
	v_mfma_f32_16x16x32_bf16 v[24:27], v[136:139], v[204:207], v[24:27]
	v_mfma_f32_16x16x32_bf16 v[12:15], v[128:131], v[212:215], v[12:15]
	v_mfma_f32_16x16x32_bf16 v[8:11], v[136:139], v[212:215], v[8:11]
	v_mfma_f32_16x16x32_bf16 v[60:63], v[132:135], v[192:195], v[60:63]
	v_mfma_f32_16x16x32_bf16 v[56:59], v[140:143], v[192:195], v[56:59]
	v_mfma_f32_16x16x32_bf16 v[44:47], v[132:135], v[200:203], v[44:47]
	v_mfma_f32_16x16x32_bf16 v[40:43], v[140:143], v[200:203], v[40:43]
	v_mfma_f32_16x16x32_bf16 v[28:31], v[132:135], v[208:211], v[28:31]
	v_mfma_f32_16x16x32_bf16 v[24:27], v[140:143], v[208:211], v[24:27]
	v_mfma_f32_16x16x32_bf16 v[12:15], v[132:135], v[230:233], v[12:15]
	v_mfma_f32_16x16x32_bf16 v[8:11], v[140:143], v[230:233], v[8:11]
	v_mfma_f32_16x16x32_bf16 v[48:51], v[154:157], v[176:179], v[48:51]
	v_mfma_f32_16x16x32_bf16 v[52:55], v[168:171], v[176:179], v[52:55]
	v_mfma_f32_16x16x32_bf16 v[32:35], v[154:157], v[196:199], v[32:35]
	v_mfma_f32_16x16x32_bf16 v[36:39], v[168:171], v[196:199], v[36:39]
	v_mfma_f32_16x16x32_bf16 v[16:19], v[154:157], v[204:207], v[16:19]
	v_mfma_f32_16x16x32_bf16 v[20:23], v[168:171], v[204:207], v[20:23]
	v_mfma_f32_16x16x32_bf16 v[0:3], v[154:157], v[212:215], v[0:3]
	v_mfma_f32_16x16x32_bf16 v[4:7], v[168:171], v[212:215], v[4:7]
	v_mfma_f32_16x16x32_bf16 v[48:51], v[164:167], v[192:195], v[48:51]
	v_mfma_f32_16x16x32_bf16 v[52:55], v[172:175], v[192:195], v[52:55]
	v_mfma_f32_16x16x32_bf16 v[32:35], v[164:167], v[200:203], v[32:35]
	v_mfma_f32_16x16x32_bf16 v[36:39], v[172:175], v[200:203], v[36:39]
	v_mfma_f32_16x16x32_bf16 v[16:19], v[164:167], v[208:211], v[16:19]
	v_mfma_f32_16x16x32_bf16 v[20:23], v[172:175], v[208:211], v[20:23]
	v_mfma_f32_16x16x32_bf16 v[0:3], v[164:167], v[230:233], v[0:3]
	v_mfma_f32_16x16x32_bf16 v[4:7], v[172:175], v[230:233], v[4:7]
	s_barrier
	s_add_i32 s49, 0, 0x18000
	s_add_i32 s50, 0, 0x1c000
	v_add_u32_e32 v140, s49, v162
	v_add_u32_e32 v172, s50, v162
	ds_read_b128 v[128:131], v140
	ds_read_b128 v[132:135], v140 offset:1024
	ds_read_b128 v[136:139], v140 offset:2048
	ds_read_b128 v[140:143], v140 offset:3072
	ds_read_b128 v[154:157], v172
	ds_read_b128 v[164:167], v172 offset:1024
	ds_read_b128 v[168:171], v172 offset:2048
	ds_read_b128 v[172:175], v172 offset:3072
	s_add_u32 s26, s26, 0x40000
	s_addc_u32 s27, s27, 0
	s_mov_b32 m0, s30
	v_lshl_add_u64 v[238:239], s[26:27], 0, v[148:149]
	ds_read_b128 v[176:179], v163 offset:32768
	ds_read_b128 v[192:195], v163 offset:33792
	ds_read_b128 v[196:199], v163 offset:34816
	ds_read_b128 v[200:203], v163 offset:35840
	ds_read_b128 v[204:207], v163 offset:36864
	ds_read_b128 v[208:211], v163 offset:37888
	ds_read_b128 v[212:215], v163 offset:38912
	ds_read_b128 v[230:233], v163 offset:39936
	global_load_lds_dwordx4 v[238:239], off
	v_lshl_add_u64 v[238:239], s[26:27], 0, v[146:147]
	s_mov_b32 m0, s31
	s_nop 0
	global_load_lds_dwordx4 v[238:239], off
	s_waitcnt vmcnt(8)
	s_waitcnt lgkmcnt(0)
	s_barrier
	s_waitcnt lgkmcnt(0)
	v_mfma_f32_16x16x32_bf16 v[124:127], v[128:131], v[176:179], v[124:127]
	v_mfma_f32_16x16x32_bf16 v[120:123], v[136:139], v[176:179], v[120:123]
	v_mfma_f32_16x16x32_bf16 v[108:111], v[128:131], v[196:199], v[108:111]
	v_mfma_f32_16x16x32_bf16 v[104:107], v[136:139], v[196:199], v[104:107]
	v_mfma_f32_16x16x32_bf16 v[92:95], v[128:131], v[204:207], v[92:95]
	v_mfma_f32_16x16x32_bf16 v[88:91], v[136:139], v[204:207], v[88:91]
	v_mfma_f32_16x16x32_bf16 v[76:79], v[128:131], v[212:215], v[76:79]
	v_mfma_f32_16x16x32_bf16 v[72:75], v[136:139], v[212:215], v[72:75]
	v_mfma_f32_16x16x32_bf16 v[124:127], v[132:135], v[192:195], v[124:127]
	v_mfma_f32_16x16x32_bf16 v[120:123], v[140:143], v[192:195], v[120:123]
	v_mfma_f32_16x16x32_bf16 v[108:111], v[132:135], v[200:203], v[108:111]
	v_mfma_f32_16x16x32_bf16 v[104:107], v[140:143], v[200:203], v[104:107]
	v_mfma_f32_16x16x32_bf16 v[92:95], v[132:135], v[208:211], v[92:95]
	v_mfma_f32_16x16x32_bf16 v[88:91], v[140:143], v[208:211], v[88:91]
	v_mfma_f32_16x16x32_bf16 v[76:79], v[132:135], v[230:233], v[76:79]
	v_mfma_f32_16x16x32_bf16 v[72:75], v[140:143], v[230:233], v[72:75]
	v_mfma_f32_16x16x32_bf16 v[112:115], v[154:157], v[176:179], v[112:115]
	v_mfma_f32_16x16x32_bf16 v[116:119], v[168:171], v[176:179], v[116:119]
	v_mfma_f32_16x16x32_bf16 v[96:99], v[154:157], v[196:199], v[96:99]
	v_mfma_f32_16x16x32_bf16 v[100:103], v[168:171], v[196:199], v[100:103]
	v_mfma_f32_16x16x32_bf16 v[80:83], v[154:157], v[204:207], v[80:83]
	v_mfma_f32_16x16x32_bf16 v[84:87], v[168:171], v[204:207], v[84:87]
	v_mfma_f32_16x16x32_bf16 v[64:67], v[154:157], v[212:215], v[64:67]
	v_mfma_f32_16x16x32_bf16 v[68:71], v[168:171], v[212:215], v[68:71]
	v_mfma_f32_16x16x32_bf16 v[112:115], v[164:167], v[192:195], v[112:115]
	v_mfma_f32_16x16x32_bf16 v[116:119], v[172:175], v[192:195], v[116:119]
	v_mfma_f32_16x16x32_bf16 v[96:99], v[164:167], v[200:203], v[96:99]
	v_mfma_f32_16x16x32_bf16 v[100:103], v[172:175], v[200:203], v[100:103]
	v_mfma_f32_16x16x32_bf16 v[80:83], v[164:167], v[208:211], v[80:83]
	v_mfma_f32_16x16x32_bf16 v[84:87], v[172:175], v[208:211], v[84:87]
	v_mfma_f32_16x16x32_bf16 v[64:67], v[164:167], v[230:233], v[64:67]
	v_mfma_f32_16x16x32_bf16 v[68:71], v[172:175], v[230:233], v[68:71]
	s_barrier
; #define PG8_STAGE(bufoff, gbase, voff) do { _Pragma("unroll") for (int _i = 0; _i < 2; ++_i) \
;         __builtin_amdgcn_global_load_lds((const unsigned*)((const char*)(gbase) + (voff)[_i]), (LAS unsigned*)(lds + (bufoff) + ldsw + _i * 8192), 16, 0, 0); } while (0)
; #define PG8_LDA(dst, b, h) do { _Pragma("unroll") for (int m = 0; m < 4; ++m) _Pragma("unroll") for (int k = 0; k < 2; ++k) dst[m][k] = *(const LAS bf16x8*)(lds + PG8_SA(b, h) + aoff + m * 2048 + k * 1024); } while (0)
; #define PG8_MMA(ai, bj, At, Bt) do { __builtin_amdgcn_s_setprio(1); _Pragma("unroll") for (int m = 0; m < 4; ++m) _Pragma("unroll") for (int n = 0; n < 2; ++n) _Pragma("unroll") for (int k = 0; k < 2; ++k) \
;         acc[ai][bj][m][n] = __builtin_amdgcn_mfma_f32_16x16x32_bf16(Bt[n][k], At[m][k], acc[ai][bj][m][n], 0, 0, 0); __builtin_amdgcn_s_setprio(0); } while (0)
; #define PG8_WAIT_V(n) asm volatile("s_waitcnt vmcnt(" #n ")" ::: "memory")
; #define PG8_WAIT_L(n) asm volatile("s_waitcnt lgkmcnt(" #n ")" ::: "memory")
; #define PG8_BAR __builtin_amdgcn_s_barrier()
; #define PG8_SCHED __builtin_amdgcn_sched_barrier(0)
; template <class Epi, class Sched>
; __device__ __forceinline__ void gemm_phase(LAS unsigned char* lds, const Gemm g, const Sched& S, const Epi& E) {
;     ...
;             PG8_LDA(At, 1, 1); PG8_STAGE(PG8_SB(1, 0), b3, voffB); PG8_STAGE(PG8_SB(1, 1), b3 + hstep, voffB); PG8_STAGE(PG8_SA(1, 0), a3, voffA);
;             PG8_WAIT_V(8); PG8_WAIT_L(0); PG8_BAR; PG8_MMA(1, 0, At, B0); PG8_MMA(1, 1, At, B1); PG8_BAR; PG8_SCHED;
;         }
;         if (wr == 0) PG8_BAR;
	s_add_i32 s26, s49, s8
	v_lshl_add_u64 v[158:159], v[158:159], 0, s[84:85]
	s_mov_b32 m0, s26
	ds_read_b128 v[176:179], v163 offset:49152
	ds_read_b128 v[192:195], v163 offset:50176
	ds_read_b128 v[196:199], v163 offset:51200
	ds_read_b128 v[200:203], v163 offset:52224
	ds_read_b128 v[204:207], v163 offset:53248
	ds_read_b128 v[208:211], v163 offset:54272
	ds_read_b128 v[212:215], v163 offset:55296
	ds_read_b128 v[230:233], v163 offset:56320
	global_load_lds_dwordx4 v[158:159], off
	s_add_i32 m0, s26, 0x2000
	s_add_u32 s24, s24, 0x40080
	v_lshl_add_u64 v[158:159], v[216:217], 0, s[84:85]
	s_addc_u32 s25, s25, 0
	s_add_i32 s26, s50, s8
	global_load_lds_dwordx4 v[158:159], off
	v_lshl_add_u64 v[158:159], s[24:25], 0, v[184:185]
	s_mov_b32 m0, s26
	s_nop 0
	global_load_lds_dwordx4 v[158:159], off
	v_lshl_add_u64 v[158:159], s[24:25], 0, v[144:145]
	s_add_i32 m0, s26, 0x2000
	s_nop 0
	global_load_lds_dwordx4 v[158:159], off
	v_lshl_add_u64 v[158:159], v[234:235], 0, s[84:85]
	s_mov_b32 m0, s36
	s_nop 0
	global_load_lds_dwordx4 v[158:159], off
	v_lshl_add_u64 v[158:159], v[236:237], 0, s[84:85]
	s_mov_b32 m0, s37
	s_nop 0
	global_load_lds_dwordx4 v[158:159], off
	s_waitcnt vmcnt(8)
	s_waitcnt lgkmcnt(0)
	s_barrier
	s_waitcnt lgkmcnt(0)
	v_mfma_f32_16x16x32_bf16 v[60:63], v[128:131], v[176:179], v[60:63]
	v_mfma_f32_16x16x32_bf16 v[56:59], v[136:139], v[176:179], v[56:59]
	v_mfma_f32_16x16x32_bf16 v[44:47], v[128:131], v[196:199], v[44:47]
	v_mfma_f32_16x16x32_bf16 v[40:43], v[136:139], v[196:199], v[40:43]
	v_mfma_f32_16x16x32_bf16 v[28:31], v[128:131], v[204:207], v[28:31]
	v_mfma_f32_16x16x32_bf16 v[24:27], v[136:139], v[204:207], v[24:27]
	v_mfma_f32_16x16x32_bf16 v[12:15], v[128:131], v[212:215], v[12:15]
	v_mfma_f32_16x16x32_bf16 v[8:11], v[136:139], v[212:215], v[8:11]
	v_mfma_f32_16x16x32_bf16 v[60:63], v[132:135], v[192:195], v[60:63]
	v_mfma_f32_16x16x32_bf16 v[56:59], v[140:143], v[192:195], v[56:59]
	v_mfma_f32_16x16x32_bf16 v[44:47], v[132:135], v[200:203], v[44:47]
	v_mfma_f32_16x16x32_bf16 v[40:43], v[140:143], v[200:203], v[40:43]
	v_mfma_f32_16x16x32_bf16 v[28:31], v[132:135], v[208:211], v[28:31]
	v_mfma_f32_16x16x32_bf16 v[24:27], v[140:143], v[208:211], v[24:27]
	v_mfma_f32_16x16x32_bf16 v[12:15], v[132:135], v[230:233], v[12:15]
	v_mfma_f32_16x16x32_bf16 v[8:11], v[140:143], v[230:233], v[8:11]
	v_mfma_f32_16x16x32_bf16 v[48:51], v[154:157], v[176:179], v[48:51]
	v_mfma_f32_16x16x32_bf16 v[52:55], v[168:171], v[176:179], v[52:55]
	v_mfma_f32_16x16x32_bf16 v[32:35], v[154:157], v[196:199], v[32:35]
	v_mfma_f32_16x16x32_bf16 v[36:39], v[168:171], v[196:199], v[36:39]
	v_mfma_f32_16x16x32_bf16 v[16:19], v[154:157], v[204:207], v[16:19]
	v_mfma_f32_16x16x32_bf16 v[20:23], v[168:171], v[204:207], v[20:23]
	v_mfma_f32_16x16x32_bf16 v[0:3], v[154:157], v[212:215], v[0:3]
	v_mfma_f32_16x16x32_bf16 v[4:7], v[168:171], v[212:215], v[4:7]
	v_mfma_f32_16x16x32_bf16 v[48:51], v[164:167], v[192:195], v[48:51]
	v_mfma_f32_16x16x32_bf16 v[52:55], v[172:175], v[192:195], v[52:55]
	v_mfma_f32_16x16x32_bf16 v[32:35], v[164:167], v[200:203], v[32:35]
	v_mfma_f32_16x16x32_bf16 v[36:39], v[172:175], v[200:203], v[36:39]
	v_mfma_f32_16x16x32_bf16 v[16:19], v[164:167], v[208:211], v[16:19]
	v_mfma_f32_16x16x32_bf16 v[20:23], v[172:175], v[208:211], v[20:23]
	v_mfma_f32_16x16x32_bf16 v[0:3], v[164:167], v[230:233], v[0:3]
	v_mfma_f32_16x16x32_bf16 v[4:7], v[172:175], v[230:233], v[4:7]
	s_barrier
	s_add_i32 s48, s48, 2
	s_add_u32 s22, s22, 0x100
	s_addc_u32 s23, s23, 0
	s_add_u32 s46, s46, 0x100
	s_addc_u32 s47, s47, 0
	s_cmp_gt_u32 s48, 13
	s_cbranch_scc0 .LBB0_744
	s_setprio 0
	s_and_b64 vcc, exec, s[6:7]
	s_cbranch_vccz .LBB0_747
	s_barrier
